# waits-to-first-consumer in the five GEMM K-loops: the next-tile pointer scalars (add/addc/cmp/4 cselect) moved from the loop head to behind the 16-read LDS burst, in front of the closing vmcnt wait, s
# baseline (speedup 1.0000x reference)
; #define PG8_STAGE(bufoff, gbase, voff) do { _Pragma("unroll") for (int _i = 0; _i < 2; ++_i) \
;         __builtin_amdgcn_global_load_lds((const unsigned*)((const char*)(gbase) + (voff)[_i]), (PG8_LAS unsigned*)(lds + (bufoff) + ldsw + _i * 8192), 16, 0, 0); } while (0)
; #define PG8_LDA(dst, b, h) do { _Pragma("unroll") for (int m = 0; m < 4; ++m) _Pragma("unroll") for (int k = 0; k < 2; ++k) dst[m][k] = *(const PG8_LAS bf16x8*)(lds + PG8_SA(b, h) + aoff + m * 2048 + k * 1024); } while (0)
; #define PG8_LDB(dst, b, h) do { _Pragma("unroll") for (int n = 0; n < 2; ++n) _Pragma("unroll") for (int k = 0; k < 2; ++k) dst[n][k] = *(const PG8_LAS bf16x8*)(lds + PG8_SB(b, h) + boff + n * 2048 + k * 1024); } while (0)
; #define PG8_MMA(ai, bj, At, Bt) do { __builtin_amdgcn_s_setprio(1); _Pragma("unroll") for (int m = 0; m < 4; ++m) _Pragma("unroll") for (int n = 0; n < 2; ++n) _Pragma("unroll") for (int k = 0; k < 2; ++k) \
;         acc[ai][bj][m][n] = __builtin_amdgcn_mfma_f32_16x16x32_bf16(Bt[n][k], At[m][k], acc[ai][bj][m][n], 0, 0, 0); __builtin_amdgcn_s_setprio(0); } while (0)
; #define PG8_WAIT_V(n) asm volatile("s_waitcnt vmcnt(" #n ")" ::: "memory")
; #define PG8_BAR __builtin_amdgcn_s_barrier()
; template <class Epi, class Sched, bool ALIGN_EPI = false, bool SP2 = false>
; __device__ __forceinline__ void gemm_phase(PG8_LAS unsigned char* lds, const Gemm g, const Sched& S, const Epi& E, int wid0) {
;     ...
;         for (int t = 0; t < nt; t += 2) {
;             const bool last = (t == nt - 2);
;             const char* a1 = cA + (size_t)(t + 1) * kstep;
;             const char* a2 = last ? nA : cA + (size_t)(t + 2) * kstep; const char* b2 = last ? nB : cB + (size_t)(t + 2) * kstep;
;             const char* a3 = a2 + kstep; const char* b3 = b2 + kstep;
;             if (last && has_next) S.a_ready(nxt);
;             if constexpr (SP2) {
;             PG8_LDB(B0, 0, 0); PG8_LDB(B1, 0, 1); PG8_SCHED; PG8_LDA(At, 0, 0); PG8_STAGE(PG8_SA(1, 1), a1 + hstep, voffA);
;             PG8_WAIT_V(8); PG8_WAIT_L(0); PG8_BAR; PG8_MMA(0, 0, At, B0); PG8_MMA(0, 1, At, B1); PG8_BAR; PG8_SCHED;
;             PG8_LDA(At, 0, 1); PG8_STAGE(PG8_SB(0, 0), b2, voffB); PG8_STAGE(PG8_SB(0, 1), b2 + hstep, voffB); PG8_STAGE(PG8_SA(0, 0), a2, voffA);
;             PG8_WAIT_V(8); PG8_WAIT_L(0); PG8_BAR; PG8_MMA(1, 0, At, B0); PG8_MMA(1, 1, At, B1); PG8_BAR; PG8_SCHED;
.LBB0_143:
	s_add_i32 s65, 0, 0x10000
	s_add_i32 s66, 0, 0x14000
	v_add_u32_e32 v140, s65, v164
	v_add_u32_e32 v162, s66, v164
	ds_read_b128 v[128:131], v140
	ds_read_b128 v[132:135], v140 offset:1024
	ds_read_b128 v[136:139], v140 offset:2048
	ds_read_b128 v[140:143], v140 offset:3072
	ds_read_b128 v[158:161], v162
	ds_read_b128 v[166:169], v162 offset:1024
	ds_read_b128 v[170:173], v162 offset:2048
	ds_read_b128 v[174:177], v162 offset:3072
	v_lshl_add_u64 v[162:163], s[84:85], 0, v[156:157]
	s_add_i32 m0, s94, 0xc000
	ds_read_b128 v[178:181], v165
	ds_read_b128 v[182:185], v165 offset:1024
	ds_read_b128 v[186:189], v165 offset:2048
	ds_read_b128 v[198:201], v165 offset:3072
	ds_read_b128 v[202:205], v165 offset:4096
	ds_read_b128 v[206:209], v165 offset:5120
	ds_read_b128 v[210:213], v165 offset:6144
	ds_read_b128 v[220:223], v165 offset:7168
	global_load_lds_dwordx4 v[162:163], off
	v_lshl_add_u64 v[162:163], s[84:85], 0, v[154:155]
	s_add_i32 m0, s94, 0xe000
	s_nop 0
	global_load_lds_dwordx4 v[162:163], off
	s_add_u32 s26, s84, 0xfffc0080
	s_addc_u32 s27, s85, -1
	s_cmp_eq_u32 s64, 12
	s_cselect_b32 vcc_hi, s45, s27
	s_cselect_b32 vcc_lo, s77, s26
	s_cselect_b32 s87, s75, s11
	s_cselect_b32 s86, s83, s10
	s_waitcnt vmcnt(8)
	s_waitcnt lgkmcnt(0)
	s_barrier
	s_setprio 1
	s_waitcnt lgkmcnt(0)
	v_mfma_f32_16x16x32_bf16 v[124:127], v[128:131], v[178:181], v[124:127]
	v_mfma_f32_16x16x32_bf16 v[120:123], v[136:139], v[178:181], v[120:123]
	v_mfma_f32_16x16x32_bf16 v[108:111], v[128:131], v[186:189], v[108:111]
	v_mfma_f32_16x16x32_bf16 v[104:107], v[136:139], v[186:189], v[104:107]
	v_mfma_f32_16x16x32_bf16 v[92:95], v[128:131], v[202:205], v[92:95]
	v_mfma_f32_16x16x32_bf16 v[88:91], v[136:139], v[202:205], v[88:91]
	v_mfma_f32_16x16x32_bf16 v[76:79], v[128:131], v[210:213], v[76:79]
	v_mfma_f32_16x16x32_bf16 v[72:75], v[136:139], v[210:213], v[72:75]
	v_mfma_f32_16x16x32_bf16 v[124:127], v[132:135], v[182:185], v[124:127]
	v_mfma_f32_16x16x32_bf16 v[120:123], v[140:143], v[182:185], v[120:123]
	v_mfma_f32_16x16x32_bf16 v[108:111], v[132:135], v[198:201], v[108:111]
	v_mfma_f32_16x16x32_bf16 v[104:107], v[140:143], v[198:201], v[104:107]
	v_mfma_f32_16x16x32_bf16 v[92:95], v[132:135], v[206:209], v[92:95]
	v_mfma_f32_16x16x32_bf16 v[88:91], v[140:143], v[206:209], v[88:91]
	v_mfma_f32_16x16x32_bf16 v[76:79], v[132:135], v[220:223], v[76:79]
	v_mfma_f32_16x16x32_bf16 v[72:75], v[140:143], v[220:223], v[72:75]
	s_setprio 0
	s_setprio 1
	v_mfma_f32_16x16x32_bf16 v[116:119], v[158:161], v[178:181], v[116:119]
	v_mfma_f32_16x16x32_bf16 v[112:115], v[170:173], v[178:181], v[112:115]
	v_mfma_f32_16x16x32_bf16 v[100:103], v[158:161], v[186:189], v[100:103]
	v_mfma_f32_16x16x32_bf16 v[96:99], v[170:173], v[186:189], v[96:99]
	v_mfma_f32_16x16x32_bf16 v[84:87], v[158:161], v[202:205], v[84:87]
	v_mfma_f32_16x16x32_bf16 v[80:83], v[170:173], v[202:205], v[80:83]
	v_mfma_f32_16x16x32_bf16 v[68:71], v[158:161], v[210:213], v[68:71]
	v_mfma_f32_16x16x32_bf16 v[64:67], v[170:173], v[210:213], v[64:67]
	v_mfma_f32_16x16x32_bf16 v[116:119], v[166:169], v[182:185], v[116:119]
	v_mfma_f32_16x16x32_bf16 v[112:115], v[174:177], v[182:185], v[112:115]
	v_mfma_f32_16x16x32_bf16 v[100:103], v[166:169], v[198:201], v[100:103]
	v_mfma_f32_16x16x32_bf16 v[96:99], v[174:177], v[198:201], v[96:99]
	v_mfma_f32_16x16x32_bf16 v[84:87], v[166:169], v[206:209], v[84:87]
	v_mfma_f32_16x16x32_bf16 v[80:83], v[174:177], v[206:209], v[80:83]
	v_mfma_f32_16x16x32_bf16 v[68:71], v[166:169], v[220:223], v[68:71]
	v_mfma_f32_16x16x32_bf16 v[64:67], v[174:177], v[220:223], v[64:67]
	s_barrier
	s_setprio 0
	s_add_i32 s26, s65, s93
	v_lshl_add_u64 v[162:163], s[86:87], 0, v[148:149]
	s_mov_b32 m0, s26
	ds_read_b128 v[178:181], v165 offset:16384
	ds_read_b128 v[182:185], v165 offset:17408
	ds_read_b128 v[186:189], v165 offset:18432
	ds_read_b128 v[198:201], v165 offset:19456
	ds_read_b128 v[202:205], v165 offset:20480
	ds_read_b128 v[206:209], v165 offset:21504
	ds_read_b128 v[210:213], v165 offset:22528
	ds_read_b128 v[220:223], v165 offset:23552
	global_load_lds_dwordx4 v[162:163], off
	s_add_i32 m0, s26, 0x2000
	s_add_u32 s26, s86, 0x40000
	v_lshl_add_u64 v[190:191], s[86:87], 0, v[144:145]
	s_addc_u32 s27, s87, 0
	s_add_i32 s65, s66, s93
	global_load_lds_dwordx4 v[190:191], off
	v_lshl_add_u64 v[194:195], s[26:27], 0, v[148:149]
	s_mov_b32 m0, s65
	v_lshl_add_u64 v[196:197], vcc, 0, v[146:147]
	global_load_lds_dwordx4 v[194:195], off
	v_lshl_add_u64 v[194:195], s[26:27], 0, v[144:145]
	s_add_i32 m0, s65, 0x2000
	s_nop 0
	global_load_lds_dwordx4 v[194:195], off
	v_lshl_add_u64 v[194:195], vcc, 0, v[150:151]
	s_mov_b32 m0, s94
	s_nop 0
	global_load_lds_dwordx4 v[194:195], off
	s_mov_b32 m0, s95
	s_nop 0
	global_load_lds_dwordx4 v[196:197], off
	s_waitcnt vmcnt(8)
	s_waitcnt lgkmcnt(0)
	s_barrier
; #define PG8_STAGE(bufoff, gbase, voff) do { _Pragma("unroll") for (int _i = 0; _i < 2; ++_i) \
;         __builtin_amdgcn_global_load_lds((const unsigned*)((const char*)(gbase) + (voff)[_i]), (PG8_LAS unsigned*)(lds + (bufoff) + ldsw + _i * 8192), 16, 0, 0); } while (0)
; #define PG8_LDA(dst, b, h) do { _Pragma("unroll") for (int m = 0; m < 4; ++m) _Pragma("unroll") for (int k = 0; k < 2; ++k) dst[m][k] = *(const PG8_LAS bf16x8*)(lds + PG8_SA(b, h) + aoff + m * 2048 + k * 1024); } while (0)
; #define PG8_LDB(dst, b, h) do { _Pragma("unroll") for (int n = 0; n < 2; ++n) _Pragma("unroll") for (int k = 0; k < 2; ++k) dst[n][k] = *(const PG8_LAS bf16x8*)(lds + PG8_SB(b, h) + boff + n * 2048 + k * 1024); } while (0)
; #define PG8_MMA(ai, bj, At, Bt) do { __builtin_amdgcn_s_setprio(1); _Pragma("unroll") for (int m = 0; m < 4; ++m) _Pragma("unroll") for (int n = 0; n < 2; ++n) _Pragma("unroll") for (int k = 0; k < 2; ++k) \
;         acc[ai][bj][m][n] = __builtin_amdgcn_mfma_f32_16x16x32_bf16(Bt[n][k], At[m][k], acc[ai][bj][m][n], 0, 0, 0); __builtin_amdgcn_s_setprio(0); } while (0)
; #define PG8_WAIT_V(n) asm volatile("s_waitcnt vmcnt(" #n ")" ::: "memory")
; #define PG8_WAIT_L(n) asm volatile("s_waitcnt lgkmcnt(" #n ")" ::: "memory")
; #define PG8_BAR __builtin_amdgcn_s_barrier()
; #define PG8_SCHED __builtin_amdgcn_sched_barrier(0)
; template <class Epi, class Sched, bool ALIGN_EPI = false, bool SP2 = false>
; __device__ __forceinline__ void gemm_phase(PG8_LAS unsigned char* lds, const Gemm g, const Sched& S, const Epi& E, int wid0) {
;     ...
;             PG8_WAIT_V(8); PG8_WAIT_L(0); PG8_BAR; PG8_MMA(1, 0, At, B0); PG8_MMA(1, 1, At, B1); PG8_BAR; PG8_SCHED;
;             PG8_LDB(B0, 1, 0); PG8_LDB(B1, 1, 1); PG8_SCHED; PG8_LDA(At, 1, 0); PG8_STAGE(PG8_SA(0, 1), a2 + hstep, voffA);
;             PG8_WAIT_V(8); PG8_WAIT_L(0); PG8_BAR; PG8_MMA(0, 0, At, B0); PG8_MMA(0, 1, At, B1); PG8_BAR; PG8_SCHED;
;             PG8_LDA(At, 1, 1); PG8_STAGE(PG8_SB(1, 0), b3, voffB); PG8_STAGE(PG8_SB(1, 1), b3 + hstep, voffB); PG8_STAGE(PG8_SA(1, 0), a3, voffA);
	s_setprio 1
	s_waitcnt lgkmcnt(0)
	v_mfma_f32_16x16x32_bf16 v[60:63], v[128:131], v[178:181], v[60:63]
	v_mfma_f32_16x16x32_bf16 v[56:59], v[136:139], v[178:181], v[56:59]
	v_mfma_f32_16x16x32_bf16 v[44:47], v[128:131], v[186:189], v[44:47]
	v_mfma_f32_16x16x32_bf16 v[40:43], v[136:139], v[186:189], v[40:43]
	v_mfma_f32_16x16x32_bf16 v[28:31], v[128:131], v[202:205], v[28:31]
	v_mfma_f32_16x16x32_bf16 v[24:27], v[136:139], v[202:205], v[24:27]
	v_mfma_f32_16x16x32_bf16 v[12:15], v[128:131], v[210:213], v[12:15]
	v_mfma_f32_16x16x32_bf16 v[8:11], v[136:139], v[210:213], v[8:11]
	v_mfma_f32_16x16x32_bf16 v[60:63], v[132:135], v[182:185], v[60:63]
	v_mfma_f32_16x16x32_bf16 v[56:59], v[140:143], v[182:185], v[56:59]
	v_mfma_f32_16x16x32_bf16 v[44:47], v[132:135], v[198:201], v[44:47]
	v_mfma_f32_16x16x32_bf16 v[40:43], v[140:143], v[198:201], v[40:43]
	v_mfma_f32_16x16x32_bf16 v[28:31], v[132:135], v[206:209], v[28:31]
	v_mfma_f32_16x16x32_bf16 v[24:27], v[140:143], v[206:209], v[24:27]
	v_mfma_f32_16x16x32_bf16 v[12:15], v[132:135], v[220:223], v[12:15]
	v_mfma_f32_16x16x32_bf16 v[8:11], v[140:143], v[220:223], v[8:11]
	s_setprio 0
	s_setprio 1
	v_mfma_f32_16x16x32_bf16 v[52:55], v[158:161], v[178:181], v[52:55]
	v_mfma_f32_16x16x32_bf16 v[48:51], v[170:173], v[178:181], v[48:51]
	v_mfma_f32_16x16x32_bf16 v[36:39], v[158:161], v[186:189], v[36:39]
	v_mfma_f32_16x16x32_bf16 v[32:35], v[170:173], v[186:189], v[32:35]
	v_mfma_f32_16x16x32_bf16 v[20:23], v[158:161], v[202:205], v[20:23]
	v_mfma_f32_16x16x32_bf16 v[16:19], v[170:173], v[202:205], v[16:19]
	v_mfma_f32_16x16x32_bf16 v[4:7], v[158:161], v[210:213], v[4:7]
	v_mfma_f32_16x16x32_bf16 v[0:3], v[170:173], v[210:213], v[0:3]
	v_mfma_f32_16x16x32_bf16 v[52:55], v[166:169], v[182:185], v[52:55]
	v_mfma_f32_16x16x32_bf16 v[48:51], v[174:177], v[182:185], v[48:51]
	v_mfma_f32_16x16x32_bf16 v[36:39], v[166:169], v[198:201], v[36:39]
	v_mfma_f32_16x16x32_bf16 v[32:35], v[174:177], v[198:201], v[32:35]
	v_mfma_f32_16x16x32_bf16 v[20:23], v[166:169], v[206:209], v[20:23]
	v_mfma_f32_16x16x32_bf16 v[16:19], v[174:177], v[206:209], v[16:19]
	v_mfma_f32_16x16x32_bf16 v[4:7], v[166:169], v[220:223], v[4:7]
	v_mfma_f32_16x16x32_bf16 v[0:3], v[174:177], v[220:223], v[0:3]
	s_barrier
	s_setprio 0
	s_add_i32 s65, 0, 0x18000
	s_add_i32 s66, 0, 0x1c000
	v_add_u32_e32 v140, s65, v164
	v_add_u32_e32 v174, s66, v164
	ds_read_b128 v[128:131], v140
	ds_read_b128 v[132:135], v140 offset:1024
	ds_read_b128 v[136:139], v140 offset:2048
	ds_read_b128 v[140:143], v140 offset:3072
	ds_read_b128 v[158:161], v174
	ds_read_b128 v[166:169], v174 offset:1024
	ds_read_b128 v[170:173], v174 offset:2048
	ds_read_b128 v[174:177], v174 offset:3072
	s_add_u32 s26, vcc_lo, 0x40000
	s_addc_u32 s27, vcc_hi, 0
	s_mov_b32 m0, s96
	v_lshl_add_u64 v[214:215], s[26:27], 0, v[150:151]
	ds_read_b128 v[178:181], v165 offset:32768
	ds_read_b128 v[182:185], v165 offset:33792
	ds_read_b128 v[186:189], v165 offset:34816
	ds_read_b128 v[198:201], v165 offset:35840
	ds_read_b128 v[202:205], v165 offset:36864
	ds_read_b128 v[206:209], v165 offset:37888
	ds_read_b128 v[210:213], v165 offset:38912
	ds_read_b128 v[220:223], v165 offset:39936
	global_load_lds_dwordx4 v[214:215], off
	v_lshl_add_u64 v[214:215], s[26:27], 0, v[146:147]
	s_mov_b32 m0, s97
	s_nop 0
	global_load_lds_dwordx4 v[214:215], off
	s_waitcnt vmcnt(8)
	s_waitcnt lgkmcnt(0)
	s_barrier
	s_setprio 1
	s_waitcnt lgkmcnt(0)
	v_mfma_f32_16x16x32_bf16 v[124:127], v[128:131], v[178:181], v[124:127]
	v_mfma_f32_16x16x32_bf16 v[120:123], v[136:139], v[178:181], v[120:123]
	v_mfma_f32_16x16x32_bf16 v[108:111], v[128:131], v[186:189], v[108:111]
	v_mfma_f32_16x16x32_bf16 v[104:107], v[136:139], v[186:189], v[104:107]
	v_mfma_f32_16x16x32_bf16 v[92:95], v[128:131], v[202:205], v[92:95]
	v_mfma_f32_16x16x32_bf16 v[88:91], v[136:139], v[202:205], v[88:91]
	v_mfma_f32_16x16x32_bf16 v[76:79], v[128:131], v[210:213], v[76:79]
	v_mfma_f32_16x16x32_bf16 v[72:75], v[136:139], v[210:213], v[72:75]
	v_mfma_f32_16x16x32_bf16 v[124:127], v[132:135], v[182:185], v[124:127]
	v_mfma_f32_16x16x32_bf16 v[120:123], v[140:143], v[182:185], v[120:123]
	v_mfma_f32_16x16x32_bf16 v[108:111], v[132:135], v[198:201], v[108:111]
	v_mfma_f32_16x16x32_bf16 v[104:107], v[140:143], v[198:201], v[104:107]
	v_mfma_f32_16x16x32_bf16 v[92:95], v[132:135], v[206:209], v[92:95]
	v_mfma_f32_16x16x32_bf16 v[88:91], v[140:143], v[206:209], v[88:91]
	v_mfma_f32_16x16x32_bf16 v[76:79], v[132:135], v[220:223], v[76:79]
	v_mfma_f32_16x16x32_bf16 v[72:75], v[140:143], v[220:223], v[72:75]
	s_setprio 0
	s_setprio 1
	v_mfma_f32_16x16x32_bf16 v[116:119], v[158:161], v[178:181], v[116:119]
	v_mfma_f32_16x16x32_bf16 v[112:115], v[170:173], v[178:181], v[112:115]
	v_mfma_f32_16x16x32_bf16 v[100:103], v[158:161], v[186:189], v[100:103]
	v_mfma_f32_16x16x32_bf16 v[96:99], v[170:173], v[186:189], v[96:99]
	v_mfma_f32_16x16x32_bf16 v[84:87], v[158:161], v[202:205], v[84:87]
	v_mfma_f32_16x16x32_bf16 v[80:83], v[170:173], v[202:205], v[80:83]
	v_mfma_f32_16x16x32_bf16 v[68:71], v[158:161], v[210:213], v[68:71]
	v_mfma_f32_16x16x32_bf16 v[64:67], v[170:173], v[210:213], v[64:67]
	v_mfma_f32_16x16x32_bf16 v[116:119], v[166:169], v[182:185], v[116:119]
	v_mfma_f32_16x16x32_bf16 v[112:115], v[174:177], v[182:185], v[112:115]
	v_mfma_f32_16x16x32_bf16 v[100:103], v[166:169], v[198:201], v[100:103]
	v_mfma_f32_16x16x32_bf16 v[96:99], v[174:177], v[198:201], v[96:99]
	v_mfma_f32_16x16x32_bf16 v[84:87], v[166:169], v[206:209], v[84:87]
	v_mfma_f32_16x16x32_bf16 v[80:83], v[174:177], v[206:209], v[80:83]
	v_mfma_f32_16x16x32_bf16 v[68:71], v[166:169], v[220:223], v[68:71]
	v_mfma_f32_16x16x32_bf16 v[64:67], v[174:177], v[220:223], v[64:67]
	s_barrier
; #define PG8_STAGE(bufoff, gbase, voff) do { _Pragma("unroll") for (int _i = 0; _i < 2; ++_i) \
;         __builtin_amdgcn_global_load_lds((const unsigned*)((const char*)(gbase) + (voff)[_i]), (PG8_LAS unsigned*)(lds + (bufoff) + ldsw + _i * 8192), 16, 0, 0); } while (0)
; #define PG8_LDA(dst, b, h) do { _Pragma("unroll") for (int m = 0; m < 4; ++m) _Pragma("unroll") for (int k = 0; k < 2; ++k) dst[m][k] = *(const PG8_LAS bf16x8*)(lds + PG8_SA(b, h) + aoff + m * 2048 + k * 1024); } while (0)
; #define PG8_MMA(ai, bj, At, Bt) do { __builtin_amdgcn_s_setprio(1); _Pragma("unroll") for (int m = 0; m < 4; ++m) _Pragma("unroll") for (int n = 0; n < 2; ++n) _Pragma("unroll") for (int k = 0; k < 2; ++k) \
;         acc[ai][bj][m][n] = __builtin_amdgcn_mfma_f32_16x16x32_bf16(Bt[n][k], At[m][k], acc[ai][bj][m][n], 0, 0, 0); __builtin_amdgcn_s_setprio(0); } while (0)
; #define PG8_WAIT_V(n) asm volatile("s_waitcnt vmcnt(" #n ")" ::: "memory")
; #define PG8_WAIT_L(n) asm volatile("s_waitcnt lgkmcnt(" #n ")" ::: "memory")
; #define PG8_BAR __builtin_amdgcn_s_barrier()
; #define PG8_SCHED __builtin_amdgcn_sched_barrier(0)
; template <class Epi, class Sched, bool ALIGN_EPI = false, bool SP2 = false>
; __device__ __forceinline__ void gemm_phase(PG8_LAS unsigned char* lds, const Gemm g, const Sched& S, const Epi& E, int wid0) {
;     ...
;             PG8_WAIT_V(8); PG8_WAIT_L(0); PG8_BAR; PG8_MMA(0, 0, At, B0); PG8_MMA(0, 1, At, B1); PG8_BAR; PG8_SCHED;
;             PG8_LDA(At, 1, 1); PG8_STAGE(PG8_SB(1, 0), b3, voffB); PG8_STAGE(PG8_SB(1, 1), b3 + hstep, voffB); PG8_STAGE(PG8_SA(1, 0), a3, voffA);
;             PG8_WAIT_V(8); PG8_WAIT_L(0); PG8_BAR; PG8_MMA(1, 0, At, B0); PG8_MMA(1, 1, At, B1); PG8_BAR; PG8_SCHED;
	s_setprio 0
	s_add_i32 s26, s65, s93
	v_lshl_add_u64 v[162:163], v[162:163], 0, s[30:31]
	s_mov_b32 m0, s26
	ds_read_b128 v[178:181], v165 offset:49152
	ds_read_b128 v[182:185], v165 offset:50176
	ds_read_b128 v[186:189], v165 offset:51200
	ds_read_b128 v[198:201], v165 offset:52224
	ds_read_b128 v[202:205], v165 offset:53248
	ds_read_b128 v[206:209], v165 offset:54272
	ds_read_b128 v[210:213], v165 offset:55296
	ds_read_b128 v[220:223], v165 offset:56320
	global_load_lds_dwordx4 v[162:163], off
	s_add_i32 m0, s26, 0x2000
	s_add_u32 s26, s86, 0x40080
	v_lshl_add_u64 v[162:163], v[190:191], 0, s[30:31]
	s_addc_u32 s27, s87, 0
	s_add_i32 s65, s66, s93
	global_load_lds_dwordx4 v[162:163], off
	v_lshl_add_u64 v[162:163], s[26:27], 0, v[148:149]
	s_mov_b32 m0, s65
	s_nop 0
	global_load_lds_dwordx4 v[162:163], off
	v_lshl_add_u64 v[162:163], s[26:27], 0, v[144:145]
	s_add_i32 m0, s65, 0x2000
	s_nop 0
	global_load_lds_dwordx4 v[162:163], off
	v_lshl_add_u64 v[162:163], v[194:195], 0, s[30:31]
	s_mov_b32 m0, s4
	s_nop 0
	global_load_lds_dwordx4 v[162:163], off
	v_lshl_add_u64 v[162:163], v[196:197], 0, s[30:31]
	s_mov_b32 m0, s5
	s_nop 0
	global_load_lds_dwordx4 v[162:163], off
	s_waitcnt vmcnt(8)
	s_waitcnt lgkmcnt(0)
	s_barrier
	s_setprio 1
	s_waitcnt lgkmcnt(0)
	v_mfma_f32_16x16x32_bf16 v[60:63], v[128:131], v[178:181], v[60:63]
	v_mfma_f32_16x16x32_bf16 v[56:59], v[136:139], v[178:181], v[56:59]
	v_mfma_f32_16x16x32_bf16 v[44:47], v[128:131], v[186:189], v[44:47]
	v_mfma_f32_16x16x32_bf16 v[40:43], v[136:139], v[186:189], v[40:43]
	v_mfma_f32_16x16x32_bf16 v[28:31], v[128:131], v[202:205], v[28:31]
	v_mfma_f32_16x16x32_bf16 v[24:27], v[136:139], v[202:205], v[24:27]
	v_mfma_f32_16x16x32_bf16 v[12:15], v[128:131], v[210:213], v[12:15]
	v_mfma_f32_16x16x32_bf16 v[8:11], v[136:139], v[210:213], v[8:11]
	v_mfma_f32_16x16x32_bf16 v[60:63], v[132:135], v[182:185], v[60:63]
	v_mfma_f32_16x16x32_bf16 v[56:59], v[140:143], v[182:185], v[56:59]
	v_mfma_f32_16x16x32_bf16 v[44:47], v[132:135], v[198:201], v[44:47]
	v_mfma_f32_16x16x32_bf16 v[40:43], v[140:143], v[198:201], v[40:43]
	v_mfma_f32_16x16x32_bf16 v[28:31], v[132:135], v[206:209], v[28:31]
	v_mfma_f32_16x16x32_bf16 v[24:27], v[140:143], v[206:209], v[24:27]
	v_mfma_f32_16x16x32_bf16 v[12:15], v[132:135], v[220:223], v[12:15]
	v_mfma_f32_16x16x32_bf16 v[8:11], v[140:143], v[220:223], v[8:11]
	s_setprio 0
	s_setprio 1
	v_mfma_f32_16x16x32_bf16 v[52:55], v[158:161], v[178:181], v[52:55]
	v_mfma_f32_16x16x32_bf16 v[48:51], v[170:173], v[178:181], v[48:51]
	v_mfma_f32_16x16x32_bf16 v[36:39], v[158:161], v[186:189], v[36:39]
	v_mfma_f32_16x16x32_bf16 v[32:35], v[170:173], v[186:189], v[32:35]
	v_mfma_f32_16x16x32_bf16 v[20:23], v[158:161], v[202:205], v[20:23]
	v_mfma_f32_16x16x32_bf16 v[16:19], v[170:173], v[202:205], v[16:19]
	v_mfma_f32_16x16x32_bf16 v[4:7], v[158:161], v[210:213], v[4:7]
	v_mfma_f32_16x16x32_bf16 v[0:3], v[170:173], v[210:213], v[0:3]
	v_mfma_f32_16x16x32_bf16 v[52:55], v[166:169], v[182:185], v[52:55]
	v_mfma_f32_16x16x32_bf16 v[48:51], v[174:177], v[182:185], v[48:51]
	v_mfma_f32_16x16x32_bf16 v[36:39], v[166:169], v[198:201], v[36:39]
	v_mfma_f32_16x16x32_bf16 v[32:35], v[174:177], v[198:201], v[32:35]
	v_mfma_f32_16x16x32_bf16 v[20:23], v[166:169], v[206:209], v[20:23]
	v_mfma_f32_16x16x32_bf16 v[16:19], v[174:177], v[206:209], v[16:19]
	v_mfma_f32_16x16x32_bf16 v[4:7], v[166:169], v[220:223], v[4:7]
	v_mfma_f32_16x16x32_bf16 v[0:3], v[174:177], v[220:223], v[0:3]
	s_barrier
	s_setprio 0
	s_add_i32 s64, s64, 2
	s_add_u32 s10, s10, 0x100
	s_addc_u32 s11, s11, 0
	s_add_u32 s84, s84, 0x100
	s_addc_u32 s85, s85, 0
	s_cmp_gt_u32 s64, 13
	s_cbranch_scc0 .LBB0_143
	s_and_b64 vcc, exec, s[72:73]
	s_cbranch_vccz .LBB0_146
	s_barrier

; #define PG8_STAGE(bufoff, gbase, voff) do { _Pragma("unroll") for (int _i = 0; _i < 2; ++_i) \
;         __builtin_amdgcn_global_load_lds((const unsigned*)((const char*)(gbase) + (voff)[_i]), (PG8_LAS unsigned*)(lds + (bufoff) + ldsw + _i * 8192), 16, 0, 0); } while (0)
; #define PG8_LDA(dst, b, h) do { _Pragma("unroll") for (int m = 0; m < 4; ++m) _Pragma("unroll") for (int k = 0; k < 2; ++k) dst[m][k] = *(const PG8_LAS bf16x8*)(lds + PG8_SA(b, h) + aoff + m * 2048 + k * 1024); } while (0)
; #define PG8_LDB(dst, b, h) do { _Pragma("unroll") for (int n = 0; n < 2; ++n) _Pragma("unroll") for (int k = 0; k < 2; ++k) dst[n][k] = *(const PG8_LAS bf16x8*)(lds + PG8_SB(b, h) + boff + n * 2048 + k * 1024); } while (0)
; #define PG8_MMA(ai, bj, At, Bt) do { __builtin_amdgcn_s_setprio(1); _Pragma("unroll") for (int m = 0; m < 4; ++m) _Pragma("unroll") for (int n = 0; n < 2; ++n) _Pragma("unroll") for (int k = 0; k < 2; ++k) \
;         acc[ai][bj][m][n] = __builtin_amdgcn_mfma_f32_16x16x32_bf16(Bt[n][k], At[m][k], acc[ai][bj][m][n], 0, 0, 0); __builtin_amdgcn_s_setprio(0); } while (0)
; #define PG8_WAIT_V(n) asm volatile("s_waitcnt vmcnt(" #n ")" ::: "memory")
; #define PG8_BAR __builtin_amdgcn_s_barrier()
; template <class Epi, class Sched, bool ALIGN_EPI = false, bool SP2 = false>
; __device__ __forceinline__ void gemm_phase(PG8_LAS unsigned char* lds, const Gemm g, const Sched& S, const Epi& E, int wid0) {
;     ...
;         for (int t = 0; t < nt; t += 2) {
;             const bool last = (t == nt - 2);
;             const char* a1 = cA + (size_t)(t + 1) * kstep;
;             const char* a2 = last ? nA : cA + (size_t)(t + 2) * kstep; const char* b2 = last ? nB : cB + (size_t)(t + 2) * kstep;
;             const char* a3 = a2 + kstep; const char* b3 = b2 + kstep;
;             if (last && has_next) S.a_ready(nxt);
;             if constexpr (SP2) {
;             PG8_LDB(B0, 0, 0); PG8_LDB(B1, 0, 1); PG8_SCHED; PG8_LDA(At, 0, 0); PG8_STAGE(PG8_SA(1, 1), a1 + hstep, voffA);
;             PG8_WAIT_V(8); PG8_WAIT_L(0); PG8_BAR; PG8_MMA(0, 0, At, B0); PG8_MMA(0, 1, At, B1); PG8_BAR; PG8_SCHED;
;             PG8_LDA(At, 0, 1); PG8_STAGE(PG8_SB(0, 0), b2, voffB); PG8_STAGE(PG8_SB(0, 1), b2 + hstep, voffB); PG8_STAGE(PG8_SA(0, 0), a2, voffA);
;             PG8_WAIT_V(8); PG8_WAIT_L(0); PG8_BAR; PG8_MMA(1, 0, At, B0); PG8_MMA(1, 1, At, B1); PG8_BAR; PG8_SCHED;
.LBB0_167:
	s_add_i32 s65, 0, 0x10000
	s_add_i32 s66, 0, 0x14000
	v_add_u32_e32 v108, s65, v161
	v_add_u32_e32 v158, s66, v161
	ds_read_b128 v[96:99], v108
	ds_read_b128 v[100:103], v108 offset:1024
	ds_read_b128 v[104:107], v108 offset:2048
	ds_read_b128 v[108:111], v108 offset:3072
	ds_read_b128 v[154:157], v158
	ds_read_b128 v[164:167], v158 offset:1024
	ds_read_b128 v[168:171], v158 offset:2048
	ds_read_b128 v[172:175], v158 offset:3072
	v_lshl_add_u64 v[158:159], s[82:83], 0, v[152:153]
	s_add_i32 m0, s7, 0xc000
	ds_read_b128 v[176:179], v163
	ds_read_b128 v[180:183], v163 offset:1024
	ds_read_b128 v[184:187], v163 offset:2048
	ds_read_b128 v[188:191], v163 offset:3072
	ds_read_b128 v[198:201], v163 offset:4096
	ds_read_b128 v[202:205], v163 offset:5120
	ds_read_b128 v[206:209], v163 offset:6144
	ds_read_b128 v[210:213], v163 offset:7168
	global_load_lds_dwordx4 v[158:159], off
	v_lshl_add_u64 v[158:159], s[82:83], 0, v[150:151]
	s_add_i32 m0, s7, 0xe000
	s_nop 0
	global_load_lds_dwordx4 v[158:159], off
	s_add_u32 s26, s82, 0xfffc0080
	s_addc_u32 s27, s83, -1
	s_cmp_eq_u32 s64, 12
	s_cselect_b32 s87, s75, s27
	s_cselect_b32 s86, s94, s26
	s_cselect_b32 s85, s73, s11
	s_cselect_b32 s84, s95, s10
	s_waitcnt vmcnt(8)
	s_waitcnt lgkmcnt(0)
	s_barrier
	s_setprio 1
	s_waitcnt lgkmcnt(0)
	v_mfma_f32_16x16x32_bf16 v[140:143], v[96:99], v[176:179], v[140:143]
	v_mfma_f32_16x16x32_bf16 v[136:139], v[104:107], v[176:179], v[136:139]
	v_mfma_f32_16x16x32_bf16 v[124:127], v[96:99], v[184:187], v[124:127]
	v_mfma_f32_16x16x32_bf16 v[120:123], v[104:107], v[184:187], v[120:123]
	v_mfma_f32_16x16x32_bf16 v[92:95], v[96:99], v[198:201], v[92:95]
	v_mfma_f32_16x16x32_bf16 v[88:91], v[104:107], v[198:201], v[88:91]
	v_mfma_f32_16x16x32_bf16 v[76:79], v[96:99], v[206:209], v[76:79]
	v_mfma_f32_16x16x32_bf16 v[72:75], v[104:107], v[206:209], v[72:75]
	v_mfma_f32_16x16x32_bf16 v[140:143], v[100:103], v[180:183], v[140:143]
	v_mfma_f32_16x16x32_bf16 v[136:139], v[108:111], v[180:183], v[136:139]
	v_mfma_f32_16x16x32_bf16 v[124:127], v[100:103], v[188:191], v[124:127]
	v_mfma_f32_16x16x32_bf16 v[120:123], v[108:111], v[188:191], v[120:123]
	v_mfma_f32_16x16x32_bf16 v[92:95], v[100:103], v[202:205], v[92:95]
	v_mfma_f32_16x16x32_bf16 v[88:91], v[108:111], v[202:205], v[88:91]
	v_mfma_f32_16x16x32_bf16 v[76:79], v[100:103], v[210:213], v[76:79]
	v_mfma_f32_16x16x32_bf16 v[72:75], v[108:111], v[210:213], v[72:75]
	s_setprio 0
	s_setprio 1
	v_mfma_f32_16x16x32_bf16 v[132:135], v[154:157], v[176:179], v[132:135]
	v_mfma_f32_16x16x32_bf16 v[128:131], v[168:171], v[176:179], v[128:131]
	v_mfma_f32_16x16x32_bf16 v[116:119], v[154:157], v[184:187], v[116:119]
	v_mfma_f32_16x16x32_bf16 v[112:115], v[168:171], v[184:187], v[112:115]
	v_mfma_f32_16x16x32_bf16 v[84:87], v[154:157], v[198:201], v[84:87]
	v_mfma_f32_16x16x32_bf16 v[80:83], v[168:171], v[198:201], v[80:83]
	v_mfma_f32_16x16x32_bf16 v[68:71], v[154:157], v[206:209], v[68:71]
	v_mfma_f32_16x16x32_bf16 v[64:67], v[168:171], v[206:209], v[64:67]
	v_mfma_f32_16x16x32_bf16 v[132:135], v[164:167], v[180:183], v[132:135]
	v_mfma_f32_16x16x32_bf16 v[128:131], v[172:175], v[180:183], v[128:131]
	v_mfma_f32_16x16x32_bf16 v[116:119], v[164:167], v[188:191], v[116:119]
	v_mfma_f32_16x16x32_bf16 v[112:115], v[172:175], v[188:191], v[112:115]
	v_mfma_f32_16x16x32_bf16 v[84:87], v[164:167], v[202:205], v[84:87]
	v_mfma_f32_16x16x32_bf16 v[80:83], v[172:175], v[202:205], v[80:83]
	v_mfma_f32_16x16x32_bf16 v[68:71], v[164:167], v[210:213], v[68:71]
	v_mfma_f32_16x16x32_bf16 v[64:67], v[172:175], v[210:213], v[64:67]
	s_barrier
	s_setprio 0
	s_add_i32 s26, s65, s6
	v_lshl_add_u64 v[158:159], s[84:85], 0, v[192:193]
	s_mov_b32 m0, s26
	ds_read_b128 v[176:179], v163 offset:16384
	ds_read_b128 v[180:183], v163 offset:17408
	ds_read_b128 v[184:187], v163 offset:18432
	ds_read_b128 v[188:191], v163 offset:19456
	ds_read_b128 v[198:201], v163 offset:20480
	ds_read_b128 v[202:205], v163 offset:21504
	ds_read_b128 v[206:209], v163 offset:22528
	ds_read_b128 v[210:213], v163 offset:23552
	global_load_lds_dwordx4 v[158:159], off
	s_add_i32 m0, s26, 0x2000
	s_add_u32 s26, s84, 0x40000
	v_lshl_add_u64 v[194:195], s[84:85], 0, v[144:145]
	s_addc_u32 s27, s85, 0
	s_add_i32 s65, s66, s6
	global_load_lds_dwordx4 v[194:195], off
	v_lshl_add_u64 v[196:197], s[26:27], 0, v[192:193]
	s_mov_b32 m0, s65
	v_lshl_add_u64 v[214:215], s[86:87], 0, v[146:147]
	global_load_lds_dwordx4 v[196:197], off
	v_lshl_add_u64 v[196:197], s[26:27], 0, v[144:145]
	s_add_i32 m0, s65, 0x2000
	s_nop 0
	global_load_lds_dwordx4 v[196:197], off
	v_lshl_add_u64 v[196:197], s[86:87], 0, v[148:149]
	s_mov_b32 m0, s7
	s_nop 0
	global_load_lds_dwordx4 v[196:197], off
	s_mov_b32 m0, s44
	s_nop 0
	global_load_lds_dwordx4 v[214:215], off
	s_waitcnt vmcnt(8)
	s_waitcnt lgkmcnt(0)
	s_barrier
; #define PG8_STAGE(bufoff, gbase, voff) do { _Pragma("unroll") for (int _i = 0; _i < 2; ++_i) \
;         __builtin_amdgcn_global_load_lds((const unsigned*)((const char*)(gbase) + (voff)[_i]), (PG8_LAS unsigned*)(lds + (bufoff) + ldsw + _i * 8192), 16, 0, 0); } while (0)
; #define PG8_LDA(dst, b, h) do { _Pragma("unroll") for (int m = 0; m < 4; ++m) _Pragma("unroll") for (int k = 0; k < 2; ++k) dst[m][k] = *(const PG8_LAS bf16x8*)(lds + PG8_SA(b, h) + aoff + m * 2048 + k * 1024); } while (0)
; #define PG8_LDB(dst, b, h) do { _Pragma("unroll") for (int n = 0; n < 2; ++n) _Pragma("unroll") for (int k = 0; k < 2; ++k) dst[n][k] = *(const PG8_LAS bf16x8*)(lds + PG8_SB(b, h) + boff + n * 2048 + k * 1024); } while (0)
; #define PG8_MMA(ai, bj, At, Bt) do { __builtin_amdgcn_s_setprio(1); _Pragma("unroll") for (int m = 0; m < 4; ++m) _Pragma("unroll") for (int n = 0; n < 2; ++n) _Pragma("unroll") for (int k = 0; k < 2; ++k) \
;         acc[ai][bj][m][n] = __builtin_amdgcn_mfma_f32_16x16x32_bf16(Bt[n][k], At[m][k], acc[ai][bj][m][n], 0, 0, 0); __builtin_amdgcn_s_setprio(0); } while (0)
; #define PG8_WAIT_V(n) asm volatile("s_waitcnt vmcnt(" #n ")" ::: "memory")
; #define PG8_WAIT_L(n) asm volatile("s_waitcnt lgkmcnt(" #n ")" ::: "memory")
; #define PG8_BAR __builtin_amdgcn_s_barrier()
; #define PG8_SCHED __builtin_amdgcn_sched_barrier(0)
; template <class Epi, class Sched, bool ALIGN_EPI = false, bool SP2 = false>
; __device__ __forceinline__ void gemm_phase(PG8_LAS unsigned char* lds, const Gemm g, const Sched& S, const Epi& E, int wid0) {
;     ...
;             PG8_WAIT_V(8); PG8_WAIT_L(0); PG8_BAR; PG8_MMA(1, 0, At, B0); PG8_MMA(1, 1, At, B1); PG8_BAR; PG8_SCHED;
;             PG8_LDB(B0, 1, 0); PG8_LDB(B1, 1, 1); PG8_SCHED; PG8_LDA(At, 1, 0); PG8_STAGE(PG8_SA(0, 1), a2 + hstep, voffA);
;             PG8_WAIT_V(8); PG8_WAIT_L(0); PG8_BAR; PG8_MMA(0, 0, At, B0); PG8_MMA(0, 1, At, B1); PG8_BAR; PG8_SCHED;
;             PG8_LDA(At, 1, 1); PG8_STAGE(PG8_SB(1, 0), b3, voffB); PG8_STAGE(PG8_SB(1, 1), b3 + hstep, voffB); PG8_STAGE(PG8_SA(1, 0), a3, voffA);
	s_setprio 1
	s_waitcnt lgkmcnt(0)
	v_mfma_f32_16x16x32_bf16 v[60:63], v[96:99], v[176:179], v[60:63]
	v_mfma_f32_16x16x32_bf16 v[56:59], v[104:107], v[176:179], v[56:59]
	v_mfma_f32_16x16x32_bf16 v[48:51], v[96:99], v[184:187], v[48:51]
	v_mfma_f32_16x16x32_bf16 v[40:43], v[104:107], v[184:187], v[40:43]
	v_mfma_f32_16x16x32_bf16 v[32:35], v[96:99], v[198:201], v[32:35]
	v_mfma_f32_16x16x32_bf16 v[24:27], v[104:107], v[198:201], v[24:27]
	v_mfma_f32_16x16x32_bf16 v[16:19], v[96:99], v[206:209], v[16:19]
	v_mfma_f32_16x16x32_bf16 v[8:11], v[104:107], v[206:209], v[8:11]
	v_mfma_f32_16x16x32_bf16 v[60:63], v[100:103], v[180:183], v[60:63]
	v_mfma_f32_16x16x32_bf16 v[56:59], v[108:111], v[180:183], v[56:59]
	v_mfma_f32_16x16x32_bf16 v[48:51], v[100:103], v[188:191], v[48:51]
	v_mfma_f32_16x16x32_bf16 v[40:43], v[108:111], v[188:191], v[40:43]
	v_mfma_f32_16x16x32_bf16 v[32:35], v[100:103], v[202:205], v[32:35]
	v_mfma_f32_16x16x32_bf16 v[24:27], v[108:111], v[202:205], v[24:27]
	v_mfma_f32_16x16x32_bf16 v[16:19], v[100:103], v[210:213], v[16:19]
	v_mfma_f32_16x16x32_bf16 v[8:11], v[108:111], v[210:213], v[8:11]
	s_setprio 0
	s_setprio 1
	v_mfma_f32_16x16x32_bf16 v[52:55], v[154:157], v[176:179], v[52:55]
	v_mfma_f32_16x16x32_bf16 v[44:47], v[168:171], v[176:179], v[44:47]
	v_mfma_f32_16x16x32_bf16 v[36:39], v[154:157], v[184:187], v[36:39]
	v_mfma_f32_16x16x32_bf16 v[28:31], v[168:171], v[184:187], v[28:31]
	v_mfma_f32_16x16x32_bf16 v[20:23], v[154:157], v[198:201], v[20:23]
	v_mfma_f32_16x16x32_bf16 v[12:15], v[168:171], v[198:201], v[12:15]
	v_mfma_f32_16x16x32_bf16 v[4:7], v[154:157], v[206:209], v[4:7]
	v_mfma_f32_16x16x32_bf16 v[0:3], v[168:171], v[206:209], v[0:3]
	v_mfma_f32_16x16x32_bf16 v[52:55], v[164:167], v[180:183], v[52:55]
	v_mfma_f32_16x16x32_bf16 v[44:47], v[172:175], v[180:183], v[44:47]
	v_mfma_f32_16x16x32_bf16 v[36:39], v[164:167], v[188:191], v[36:39]
	v_mfma_f32_16x16x32_bf16 v[28:31], v[172:175], v[188:191], v[28:31]
	v_mfma_f32_16x16x32_bf16 v[20:23], v[164:167], v[202:205], v[20:23]
	v_mfma_f32_16x16x32_bf16 v[12:15], v[172:175], v[202:205], v[12:15]
	v_mfma_f32_16x16x32_bf16 v[4:7], v[164:167], v[210:213], v[4:7]
	v_mfma_f32_16x16x32_bf16 v[0:3], v[172:175], v[210:213], v[0:3]
	s_barrier
	s_setprio 0
	s_add_i32 s65, 0, 0x18000
	s_add_i32 s66, 0, 0x1c000
	v_add_u32_e32 v108, s65, v161
	v_add_u32_e32 v172, s66, v161
	ds_read_b128 v[96:99], v108
	ds_read_b128 v[100:103], v108 offset:1024
	ds_read_b128 v[104:107], v108 offset:2048
	ds_read_b128 v[108:111], v108 offset:3072
	ds_read_b128 v[154:157], v172
	ds_read_b128 v[164:167], v172 offset:1024
	ds_read_b128 v[168:171], v172 offset:2048
	ds_read_b128 v[172:175], v172 offset:3072
	s_add_u32 s26, s86, 0x40000
	s_addc_u32 s27, s87, 0
	s_mov_b32 m0, s45
	v_lshl_add_u64 v[220:221], s[26:27], 0, v[148:149]
	ds_read_b128 v[176:179], v163 offset:32768
	ds_read_b128 v[180:183], v163 offset:33792
	ds_read_b128 v[184:187], v163 offset:34816
	ds_read_b128 v[188:191], v163 offset:35840
	ds_read_b128 v[198:201], v163 offset:36864
	ds_read_b128 v[202:205], v163 offset:37888
	ds_read_b128 v[206:209], v163 offset:38912
	ds_read_b128 v[210:213], v163 offset:39936
	global_load_lds_dwordx4 v[220:221], off
	v_lshl_add_u64 v[220:221], s[26:27], 0, v[146:147]
	s_mov_b32 m0, s91
	s_nop 0
	global_load_lds_dwordx4 v[220:221], off
	s_waitcnt vmcnt(8)
	s_waitcnt lgkmcnt(0)
	s_barrier
	s_setprio 1
	s_waitcnt lgkmcnt(0)
	v_mfma_f32_16x16x32_bf16 v[140:143], v[96:99], v[176:179], v[140:143]
	v_mfma_f32_16x16x32_bf16 v[136:139], v[104:107], v[176:179], v[136:139]
	v_mfma_f32_16x16x32_bf16 v[124:127], v[96:99], v[184:187], v[124:127]
	v_mfma_f32_16x16x32_bf16 v[120:123], v[104:107], v[184:187], v[120:123]
	v_mfma_f32_16x16x32_bf16 v[92:95], v[96:99], v[198:201], v[92:95]
	v_mfma_f32_16x16x32_bf16 v[88:91], v[104:107], v[198:201], v[88:91]
	v_mfma_f32_16x16x32_bf16 v[76:79], v[96:99], v[206:209], v[76:79]
	v_mfma_f32_16x16x32_bf16 v[72:75], v[104:107], v[206:209], v[72:75]
	v_mfma_f32_16x16x32_bf16 v[140:143], v[100:103], v[180:183], v[140:143]
	v_mfma_f32_16x16x32_bf16 v[136:139], v[108:111], v[180:183], v[136:139]
	v_mfma_f32_16x16x32_bf16 v[124:127], v[100:103], v[188:191], v[124:127]
	v_mfma_f32_16x16x32_bf16 v[120:123], v[108:111], v[188:191], v[120:123]
	v_mfma_f32_16x16x32_bf16 v[92:95], v[100:103], v[202:205], v[92:95]
	v_mfma_f32_16x16x32_bf16 v[88:91], v[108:111], v[202:205], v[88:91]
	v_mfma_f32_16x16x32_bf16 v[76:79], v[100:103], v[210:213], v[76:79]
	v_mfma_f32_16x16x32_bf16 v[72:75], v[108:111], v[210:213], v[72:75]
	s_setprio 0
	s_setprio 1
	v_mfma_f32_16x16x32_bf16 v[132:135], v[154:157], v[176:179], v[132:135]
	v_mfma_f32_16x16x32_bf16 v[128:131], v[168:171], v[176:179], v[128:131]
	v_mfma_f32_16x16x32_bf16 v[116:119], v[154:157], v[184:187], v[116:119]
	v_mfma_f32_16x16x32_bf16 v[112:115], v[168:171], v[184:187], v[112:115]
	v_mfma_f32_16x16x32_bf16 v[84:87], v[154:157], v[198:201], v[84:87]
	v_mfma_f32_16x16x32_bf16 v[80:83], v[168:171], v[198:201], v[80:83]
	v_mfma_f32_16x16x32_bf16 v[68:71], v[154:157], v[206:209], v[68:71]
	v_mfma_f32_16x16x32_bf16 v[64:67], v[168:171], v[206:209], v[64:67]
	v_mfma_f32_16x16x32_bf16 v[132:135], v[164:167], v[180:183], v[132:135]
	v_mfma_f32_16x16x32_bf16 v[128:131], v[172:175], v[180:183], v[128:131]
	v_mfma_f32_16x16x32_bf16 v[116:119], v[164:167], v[188:191], v[116:119]
	v_mfma_f32_16x16x32_bf16 v[112:115], v[172:175], v[188:191], v[112:115]
	v_mfma_f32_16x16x32_bf16 v[84:87], v[164:167], v[202:205], v[84:87]
	v_mfma_f32_16x16x32_bf16 v[80:83], v[172:175], v[202:205], v[80:83]
	v_mfma_f32_16x16x32_bf16 v[68:71], v[164:167], v[210:213], v[68:71]
	v_mfma_f32_16x16x32_bf16 v[64:67], v[172:175], v[210:213], v[64:67]
	s_barrier
; #define PG8_STAGE(bufoff, gbase, voff) do { _Pragma("unroll") for (int _i = 0; _i < 2; ++_i) \
;         __builtin_amdgcn_global_load_lds((const unsigned*)((const char*)(gbase) + (voff)[_i]), (PG8_LAS unsigned*)(lds + (bufoff) + ldsw + _i * 8192), 16, 0, 0); } while (0)
; #define PG8_LDA(dst, b, h) do { _Pragma("unroll") for (int m = 0; m < 4; ++m) _Pragma("unroll") for (int k = 0; k < 2; ++k) dst[m][k] = *(const PG8_LAS bf16x8*)(lds + PG8_SA(b, h) + aoff + m * 2048 + k * 1024); } while (0)
; #define PG8_MMA(ai, bj, At, Bt) do { __builtin_amdgcn_s_setprio(1); _Pragma("unroll") for (int m = 0; m < 4; ++m) _Pragma("unroll") for (int n = 0; n < 2; ++n) _Pragma("unroll") for (int k = 0; k < 2; ++k) \
;         acc[ai][bj][m][n] = __builtin_amdgcn_mfma_f32_16x16x32_bf16(Bt[n][k], At[m][k], acc[ai][bj][m][n], 0, 0, 0); __builtin_amdgcn_s_setprio(0); } while (0)
; #define PG8_WAIT_V(n) asm volatile("s_waitcnt vmcnt(" #n ")" ::: "memory")
; #define PG8_WAIT_L(n) asm volatile("s_waitcnt lgkmcnt(" #n ")" ::: "memory")
; #define PG8_BAR __builtin_amdgcn_s_barrier()
; #define PG8_SCHED __builtin_amdgcn_sched_barrier(0)
; template <class Epi, class Sched, bool ALIGN_EPI = false, bool SP2 = false>
; __device__ __forceinline__ void gemm_phase(PG8_LAS unsigned char* lds, const Gemm g, const Sched& S, const Epi& E, int wid0) {
;     ...
;             PG8_WAIT_V(8); PG8_WAIT_L(0); PG8_BAR; PG8_MMA(0, 0, At, B0); PG8_MMA(0, 1, At, B1); PG8_BAR; PG8_SCHED;
;             PG8_LDA(At, 1, 1); PG8_STAGE(PG8_SB(1, 0), b3, voffB); PG8_STAGE(PG8_SB(1, 1), b3 + hstep, voffB); PG8_STAGE(PG8_SA(1, 0), a3, voffA);
;             PG8_WAIT_V(8); PG8_WAIT_L(0); PG8_BAR; PG8_MMA(1, 0, At, B0); PG8_MMA(1, 1, At, B1); PG8_BAR; PG8_SCHED;
	s_setprio 0
	s_add_i32 s26, s65, s6
	v_lshl_add_u64 v[158:159], v[158:159], 0, s[30:31]
	s_mov_b32 m0, s26
	ds_read_b128 v[176:179], v163 offset:49152
	ds_read_b128 v[180:183], v163 offset:50176
	ds_read_b128 v[184:187], v163 offset:51200
	ds_read_b128 v[188:191], v163 offset:52224
	ds_read_b128 v[198:201], v163 offset:53248
	ds_read_b128 v[202:205], v163 offset:54272
	ds_read_b128 v[206:209], v163 offset:55296
	ds_read_b128 v[210:213], v163 offset:56320
	global_load_lds_dwordx4 v[158:159], off
	s_add_i32 m0, s26, 0x2000
	s_add_u32 s26, s84, 0x40080
	v_lshl_add_u64 v[158:159], v[194:195], 0, s[30:31]
	s_addc_u32 s27, s85, 0
	s_add_i32 s65, s66, s6
	global_load_lds_dwordx4 v[158:159], off
	v_lshl_add_u64 v[158:159], s[26:27], 0, v[192:193]
	s_mov_b32 m0, s65
	s_nop 0
	global_load_lds_dwordx4 v[158:159], off
	v_lshl_add_u64 v[158:159], s[26:27], 0, v[144:145]
	s_add_i32 m0, s65, 0x2000
	s_nop 0
	global_load_lds_dwordx4 v[158:159], off
	v_lshl_add_u64 v[158:159], v[196:197], 0, s[30:31]
	s_mov_b32 m0, s22
	s_nop 0
	global_load_lds_dwordx4 v[158:159], off
	v_lshl_add_u64 v[158:159], v[214:215], 0, s[30:31]
	s_mov_b32 m0, s92
	s_nop 0
	global_load_lds_dwordx4 v[158:159], off
	s_waitcnt vmcnt(8)
	s_waitcnt lgkmcnt(0)
	s_barrier
	s_setprio 1
	s_waitcnt lgkmcnt(0)
	v_mfma_f32_16x16x32_bf16 v[60:63], v[96:99], v[176:179], v[60:63]
	v_mfma_f32_16x16x32_bf16 v[56:59], v[104:107], v[176:179], v[56:59]
	v_mfma_f32_16x16x32_bf16 v[48:51], v[96:99], v[184:187], v[48:51]
	v_mfma_f32_16x16x32_bf16 v[40:43], v[104:107], v[184:187], v[40:43]
	v_mfma_f32_16x16x32_bf16 v[32:35], v[96:99], v[198:201], v[32:35]
	v_mfma_f32_16x16x32_bf16 v[24:27], v[104:107], v[198:201], v[24:27]
	v_mfma_f32_16x16x32_bf16 v[16:19], v[96:99], v[206:209], v[16:19]
	v_mfma_f32_16x16x32_bf16 v[8:11], v[104:107], v[206:209], v[8:11]
	v_mfma_f32_16x16x32_bf16 v[60:63], v[100:103], v[180:183], v[60:63]
	v_mfma_f32_16x16x32_bf16 v[56:59], v[108:111], v[180:183], v[56:59]
	v_mfma_f32_16x16x32_bf16 v[48:51], v[100:103], v[188:191], v[48:51]
	v_mfma_f32_16x16x32_bf16 v[40:43], v[108:111], v[188:191], v[40:43]
	v_mfma_f32_16x16x32_bf16 v[32:35], v[100:103], v[202:205], v[32:35]
	v_mfma_f32_16x16x32_bf16 v[24:27], v[108:111], v[202:205], v[24:27]
	v_mfma_f32_16x16x32_bf16 v[16:19], v[100:103], v[210:213], v[16:19]
	v_mfma_f32_16x16x32_bf16 v[8:11], v[108:111], v[210:213], v[8:11]
	s_setprio 0
	s_setprio 1
	v_mfma_f32_16x16x32_bf16 v[52:55], v[154:157], v[176:179], v[52:55]
	v_mfma_f32_16x16x32_bf16 v[44:47], v[168:171], v[176:179], v[44:47]
	v_mfma_f32_16x16x32_bf16 v[36:39], v[154:157], v[184:187], v[36:39]
	v_mfma_f32_16x16x32_bf16 v[28:31], v[168:171], v[184:187], v[28:31]
	v_mfma_f32_16x16x32_bf16 v[20:23], v[154:157], v[198:201], v[20:23]
	v_mfma_f32_16x16x32_bf16 v[12:15], v[168:171], v[198:201], v[12:15]
	v_mfma_f32_16x16x32_bf16 v[4:7], v[154:157], v[206:209], v[4:7]
	v_mfma_f32_16x16x32_bf16 v[0:3], v[168:171], v[206:209], v[0:3]
	v_mfma_f32_16x16x32_bf16 v[52:55], v[164:167], v[180:183], v[52:55]
	v_mfma_f32_16x16x32_bf16 v[44:47], v[172:175], v[180:183], v[44:47]
	v_mfma_f32_16x16x32_bf16 v[36:39], v[164:167], v[188:191], v[36:39]
	v_mfma_f32_16x16x32_bf16 v[28:31], v[172:175], v[188:191], v[28:31]
	v_mfma_f32_16x16x32_bf16 v[20:23], v[164:167], v[202:205], v[20:23]
	v_mfma_f32_16x16x32_bf16 v[12:15], v[172:175], v[202:205], v[12:15]
	v_mfma_f32_16x16x32_bf16 v[4:7], v[164:167], v[210:213], v[4:7]
	v_mfma_f32_16x16x32_bf16 v[0:3], v[172:175], v[210:213], v[0:3]
	s_barrier
	s_setprio 0
	s_add_i32 s64, s64, 2
	s_add_u32 s10, s10, 0x100
	s_addc_u32 s11, s11, 0
	s_add_u32 s82, s82, 0x100
	s_addc_u32 s83, s83, 0
	s_cmp_gt_u32 s64, 13
	s_cbranch_scc0 .LBB0_167
	s_and_b64 vcc, exec, s[70:71]
	s_cbranch_vccz .LBB0_170
	s_barrier

; #define PG8_STAGE(bufoff, gbase, voff) do { _Pragma("unroll") for (int _i = 0; _i < 2; ++_i) \
;         __builtin_amdgcn_global_load_lds((const unsigned*)((const char*)(gbase) + (voff)[_i]), (PG8_LAS unsigned*)(lds + (bufoff) + ldsw + _i * 8192), 16, 0, 0); } while (0)
; #define PG8_LDA(dst, b, h) do { _Pragma("unroll") for (int m = 0; m < 4; ++m) _Pragma("unroll") for (int k = 0; k < 2; ++k) dst[m][k] = *(const PG8_LAS bf16x8*)(lds + PG8_SA(b, h) + aoff + m * 2048 + k * 1024); } while (0)
; #define PG8_LDB(dst, b, h) do { _Pragma("unroll") for (int n = 0; n < 2; ++n) _Pragma("unroll") for (int k = 0; k < 2; ++k) dst[n][k] = *(const PG8_LAS bf16x8*)(lds + PG8_SB(b, h) + boff + n * 2048 + k * 1024); } while (0)
; #define PG8_MMA(ai, bj, At, Bt) do { __builtin_amdgcn_s_setprio(1); _Pragma("unroll") for (int m = 0; m < 4; ++m) _Pragma("unroll") for (int n = 0; n < 2; ++n) _Pragma("unroll") for (int k = 0; k < 2; ++k) \
;         acc[ai][bj][m][n] = __builtin_amdgcn_mfma_f32_16x16x32_bf16(Bt[n][k], At[m][k], acc[ai][bj][m][n], 0, 0, 0); __builtin_amdgcn_s_setprio(0); } while (0)
; #define PG8_WAIT_V(n) asm volatile("s_waitcnt vmcnt(" #n ")" ::: "memory")
; #define PG8_BAR __builtin_amdgcn_s_barrier()
; template <class Epi, class Sched, bool ALIGN_EPI = false, bool SP2 = false>
; __device__ __forceinline__ void gemm_phase(PG8_LAS unsigned char* lds, const Gemm g, const Sched& S, const Epi& E, int wid0) {
;     ...
;         for (int t = 0; t < nt; t += 2) {
;             const bool last = (t == nt - 2);
;             const char* a1 = cA + (size_t)(t + 1) * kstep;
;             const char* a2 = last ? nA : cA + (size_t)(t + 2) * kstep; const char* b2 = last ? nB : cB + (size_t)(t + 2) * kstep;
;             const char* a3 = a2 + kstep; const char* b3 = b2 + kstep;
;             if (last && has_next) S.a_ready(nxt);
;             if constexpr (SP2) {
;             PG8_LDB(B0, 0, 0); PG8_LDB(B1, 0, 1); PG8_SCHED; PG8_LDA(At, 0, 0); PG8_STAGE(PG8_SA(1, 1), a1 + hstep, voffA);
;             PG8_WAIT_V(8); PG8_WAIT_L(0); PG8_BAR; PG8_MMA(0, 0, At, B0); PG8_MMA(0, 1, At, B1); PG8_BAR; PG8_SCHED;
;             PG8_LDA(At, 0, 1); PG8_STAGE(PG8_SB(0, 0), b2, voffB); PG8_STAGE(PG8_SB(0, 1), b2 + hstep, voffB); PG8_STAGE(PG8_SA(0, 0), a2, voffA);
;             PG8_WAIT_V(8); PG8_WAIT_L(0); PG8_BAR; PG8_MMA(1, 0, At, B0); PG8_MMA(1, 1, At, B1); PG8_BAR; PG8_SCHED;
.LBB0_377:
	s_add_i32 s65, 0, 0x10000
	s_add_i32 s66, 0, 0x14000
	v_add_u32_e32 v156, s65, v143
	v_add_u32_e32 v172, s66, v143
	ds_read_b128 v[138:141], v156
	ds_read_b128 v[148:151], v156 offset:1024
	ds_read_b128 v[152:155], v156 offset:2048
	ds_read_b128 v[156:159], v156 offset:3072
	ds_read_b128 v[160:163], v172
	ds_read_b128 v[164:167], v172 offset:1024
	ds_read_b128 v[168:171], v172 offset:2048
	ds_read_b128 v[172:175], v172 offset:3072
	v_lshl_add_u64 v[210:211], s[84:85], 0, v[136:137]
	s_add_i32 m0, s83, 0xc000
	ds_read_b128 v[176:179], v147
	ds_read_b128 v[180:183], v147 offset:1024
	ds_read_b128 v[184:187], v147 offset:2048
	ds_read_b128 v[188:191], v147 offset:3072
	ds_read_b128 v[194:197], v147 offset:4096
	ds_read_b128 v[198:201], v147 offset:5120
	ds_read_b128 v[202:205], v147 offset:6144
	ds_read_b128 v[206:209], v147 offset:7168
	global_load_lds_dwordx4 v[210:211], off
	v_lshl_add_u64 v[210:211], s[84:85], 0, v[134:135]
	s_add_i32 m0, s83, 0xe000
	s_nop 0
	global_load_lds_dwordx4 v[210:211], off
	s_add_u32 s26, s84, 0xfffc0080
	s_addc_u32 s27, s85, -1
	s_cmp_eq_u32 s64, 12
	s_cselect_b32 vcc_hi, s22, s27
	s_cselect_b32 vcc_lo, s75, s26
	s_cselect_b32 s77, s73, s11
	s_cselect_b32 s76, s81, s10
	s_waitcnt vmcnt(8)
	s_waitcnt lgkmcnt(0)
	s_barrier
	s_setprio 1
	s_waitcnt lgkmcnt(0)
	v_mfma_f32_16x16x32_bf16 v[124:127], v[138:141], v[176:179], v[124:127]
	v_mfma_f32_16x16x32_bf16 v[120:123], v[152:155], v[176:179], v[120:123]
	v_mfma_f32_16x16x32_bf16 v[108:111], v[138:141], v[184:187], v[108:111]
	v_mfma_f32_16x16x32_bf16 v[104:107], v[152:155], v[184:187], v[104:107]
	v_mfma_f32_16x16x32_bf16 v[92:95], v[138:141], v[194:197], v[92:95]
	v_mfma_f32_16x16x32_bf16 v[88:91], v[152:155], v[194:197], v[88:91]
	v_mfma_f32_16x16x32_bf16 v[76:79], v[138:141], v[202:205], v[76:79]
	v_mfma_f32_16x16x32_bf16 v[72:75], v[152:155], v[202:205], v[72:75]
	v_mfma_f32_16x16x32_bf16 v[124:127], v[148:151], v[180:183], v[124:127]
	v_mfma_f32_16x16x32_bf16 v[120:123], v[156:159], v[180:183], v[120:123]
	v_mfma_f32_16x16x32_bf16 v[108:111], v[148:151], v[188:191], v[108:111]
	v_mfma_f32_16x16x32_bf16 v[104:107], v[156:159], v[188:191], v[104:107]
	v_mfma_f32_16x16x32_bf16 v[92:95], v[148:151], v[198:201], v[92:95]
	v_mfma_f32_16x16x32_bf16 v[88:91], v[156:159], v[198:201], v[88:91]
	v_mfma_f32_16x16x32_bf16 v[76:79], v[148:151], v[206:209], v[76:79]
	v_mfma_f32_16x16x32_bf16 v[72:75], v[156:159], v[206:209], v[72:75]
	s_setprio 0
	s_setprio 1
	v_mfma_f32_16x16x32_bf16 v[116:119], v[160:163], v[176:179], v[116:119]
	v_mfma_f32_16x16x32_bf16 v[112:115], v[168:171], v[176:179], v[112:115]
	v_mfma_f32_16x16x32_bf16 v[100:103], v[160:163], v[184:187], v[100:103]
	v_mfma_f32_16x16x32_bf16 v[96:99], v[168:171], v[184:187], v[96:99]
	v_mfma_f32_16x16x32_bf16 v[84:87], v[160:163], v[194:197], v[84:87]
	v_mfma_f32_16x16x32_bf16 v[80:83], v[168:171], v[194:197], v[80:83]
	v_mfma_f32_16x16x32_bf16 v[68:71], v[160:163], v[202:205], v[68:71]
	v_mfma_f32_16x16x32_bf16 v[64:67], v[168:171], v[202:205], v[64:67]
	v_mfma_f32_16x16x32_bf16 v[116:119], v[164:167], v[180:183], v[116:119]
	v_mfma_f32_16x16x32_bf16 v[112:115], v[172:175], v[180:183], v[112:115]
	v_mfma_f32_16x16x32_bf16 v[100:103], v[164:167], v[188:191], v[100:103]
	v_mfma_f32_16x16x32_bf16 v[96:99], v[172:175], v[188:191], v[96:99]
	v_mfma_f32_16x16x32_bf16 v[84:87], v[164:167], v[198:201], v[84:87]
	v_mfma_f32_16x16x32_bf16 v[80:83], v[172:175], v[198:201], v[80:83]
	v_mfma_f32_16x16x32_bf16 v[68:71], v[164:167], v[206:209], v[68:71]
	v_mfma_f32_16x16x32_bf16 v[64:67], v[172:175], v[206:209], v[64:67]
	s_barrier
	s_setprio 0
	s_add_i32 s26, s65, s69
	v_lshl_add_u64 v[210:211], s[76:77], 0, v[192:193]
	s_mov_b32 m0, s26
	ds_read_b128 v[176:179], v147 offset:16384
	ds_read_b128 v[180:183], v147 offset:17408
	ds_read_b128 v[184:187], v147 offset:18432
	ds_read_b128 v[188:191], v147 offset:19456
	ds_read_b128 v[194:197], v147 offset:20480
	ds_read_b128 v[198:201], v147 offset:21504
	ds_read_b128 v[202:205], v147 offset:22528
	ds_read_b128 v[206:209], v147 offset:23552
	global_load_lds_dwordx4 v[210:211], off
	s_add_i32 m0, s26, 0x2000
	s_add_u32 s26, s76, 0x40000
	v_lshl_add_u64 v[212:213], s[76:77], 0, v[132:133]
	s_addc_u32 s27, s77, 0
	s_add_i32 s65, s66, s69
	global_load_lds_dwordx4 v[212:213], off
	v_lshl_add_u64 v[214:215], s[26:27], 0, v[192:193]
	s_mov_b32 m0, s65
	v_lshl_add_u64 v[220:221], vcc, 0, v[130:131]
	global_load_lds_dwordx4 v[214:215], off
	v_lshl_add_u64 v[214:215], s[26:27], 0, v[132:133]
	s_add_i32 m0, s65, 0x2000
	s_nop 0
	global_load_lds_dwordx4 v[214:215], off
	v_lshl_add_u64 v[214:215], vcc, 0, v[128:129]
	s_mov_b32 m0, s83
	s_nop 0
	global_load_lds_dwordx4 v[214:215], off
	s_mov_b32 m0, s88
	s_nop 0
	global_load_lds_dwordx4 v[220:221], off
	s_waitcnt vmcnt(8)
	s_waitcnt lgkmcnt(0)
	s_barrier
; #define PG8_STAGE(bufoff, gbase, voff) do { _Pragma("unroll") for (int _i = 0; _i < 2; ++_i) \
;         __builtin_amdgcn_global_load_lds((const unsigned*)((const char*)(gbase) + (voff)[_i]), (PG8_LAS unsigned*)(lds + (bufoff) + ldsw + _i * 8192), 16, 0, 0); } while (0)
; #define PG8_LDA(dst, b, h) do { _Pragma("unroll") for (int m = 0; m < 4; ++m) _Pragma("unroll") for (int k = 0; k < 2; ++k) dst[m][k] = *(const PG8_LAS bf16x8*)(lds + PG8_SA(b, h) + aoff + m * 2048 + k * 1024); } while (0)
; #define PG8_LDB(dst, b, h) do { _Pragma("unroll") for (int n = 0; n < 2; ++n) _Pragma("unroll") for (int k = 0; k < 2; ++k) dst[n][k] = *(const PG8_LAS bf16x8*)(lds + PG8_SB(b, h) + boff + n * 2048 + k * 1024); } while (0)
; #define PG8_MMA(ai, bj, At, Bt) do { __builtin_amdgcn_s_setprio(1); _Pragma("unroll") for (int m = 0; m < 4; ++m) _Pragma("unroll") for (int n = 0; n < 2; ++n) _Pragma("unroll") for (int k = 0; k < 2; ++k) \
;         acc[ai][bj][m][n] = __builtin_amdgcn_mfma_f32_16x16x32_bf16(Bt[n][k], At[m][k], acc[ai][bj][m][n], 0, 0, 0); __builtin_amdgcn_s_setprio(0); } while (0)
; #define PG8_WAIT_V(n) asm volatile("s_waitcnt vmcnt(" #n ")" ::: "memory")
; #define PG8_WAIT_L(n) asm volatile("s_waitcnt lgkmcnt(" #n ")" ::: "memory")
; #define PG8_BAR __builtin_amdgcn_s_barrier()
; #define PG8_SCHED __builtin_amdgcn_sched_barrier(0)
; template <class Epi, class Sched, bool ALIGN_EPI = false, bool SP2 = false>
; __device__ __forceinline__ void gemm_phase(PG8_LAS unsigned char* lds, const Gemm g, const Sched& S, const Epi& E, int wid0) {
;     ...
;             PG8_WAIT_V(8); PG8_WAIT_L(0); PG8_BAR; PG8_MMA(1, 0, At, B0); PG8_MMA(1, 1, At, B1); PG8_BAR; PG8_SCHED;
;             PG8_LDB(B0, 1, 0); PG8_LDB(B1, 1, 1); PG8_SCHED; PG8_LDA(At, 1, 0); PG8_STAGE(PG8_SA(0, 1), a2 + hstep, voffA);
;             PG8_WAIT_V(8); PG8_WAIT_L(0); PG8_BAR; PG8_MMA(0, 0, At, B0); PG8_MMA(0, 1, At, B1); PG8_BAR; PG8_SCHED;
;             PG8_LDA(At, 1, 1); PG8_STAGE(PG8_SB(1, 0), b3, voffB); PG8_STAGE(PG8_SB(1, 1), b3 + hstep, voffB); PG8_STAGE(PG8_SA(1, 0), a3, voffA);
	s_setprio 1
	s_waitcnt lgkmcnt(0)
	v_mfma_f32_16x16x32_bf16 v[60:63], v[138:141], v[176:179], v[60:63]
	v_mfma_f32_16x16x32_bf16 v[56:59], v[152:155], v[176:179], v[56:59]
	v_mfma_f32_16x16x32_bf16 v[44:47], v[138:141], v[184:187], v[44:47]
	v_mfma_f32_16x16x32_bf16 v[40:43], v[152:155], v[184:187], v[40:43]
	v_mfma_f32_16x16x32_bf16 v[28:31], v[138:141], v[194:197], v[28:31]
	v_mfma_f32_16x16x32_bf16 v[24:27], v[152:155], v[194:197], v[24:27]
	v_mfma_f32_16x16x32_bf16 v[12:15], v[138:141], v[202:205], v[12:15]
	v_mfma_f32_16x16x32_bf16 v[8:11], v[152:155], v[202:205], v[8:11]
	v_mfma_f32_16x16x32_bf16 v[60:63], v[148:151], v[180:183], v[60:63]
	v_mfma_f32_16x16x32_bf16 v[56:59], v[156:159], v[180:183], v[56:59]
	v_mfma_f32_16x16x32_bf16 v[44:47], v[148:151], v[188:191], v[44:47]
	v_mfma_f32_16x16x32_bf16 v[40:43], v[156:159], v[188:191], v[40:43]
	v_mfma_f32_16x16x32_bf16 v[28:31], v[148:151], v[198:201], v[28:31]
	v_mfma_f32_16x16x32_bf16 v[24:27], v[156:159], v[198:201], v[24:27]
	v_mfma_f32_16x16x32_bf16 v[12:15], v[148:151], v[206:209], v[12:15]
	v_mfma_f32_16x16x32_bf16 v[8:11], v[156:159], v[206:209], v[8:11]
	s_setprio 0
	s_setprio 1
	v_mfma_f32_16x16x32_bf16 v[52:55], v[160:163], v[176:179], v[52:55]
	v_mfma_f32_16x16x32_bf16 v[48:51], v[168:171], v[176:179], v[48:51]
	v_mfma_f32_16x16x32_bf16 v[36:39], v[160:163], v[184:187], v[36:39]
	v_mfma_f32_16x16x32_bf16 v[32:35], v[168:171], v[184:187], v[32:35]
	v_mfma_f32_16x16x32_bf16 v[20:23], v[160:163], v[194:197], v[20:23]
	v_mfma_f32_16x16x32_bf16 v[16:19], v[168:171], v[194:197], v[16:19]
	v_mfma_f32_16x16x32_bf16 v[4:7], v[160:163], v[202:205], v[4:7]
	v_mfma_f32_16x16x32_bf16 v[0:3], v[168:171], v[202:205], v[0:3]
	v_mfma_f32_16x16x32_bf16 v[52:55], v[164:167], v[180:183], v[52:55]
	v_mfma_f32_16x16x32_bf16 v[48:51], v[172:175], v[180:183], v[48:51]
	v_mfma_f32_16x16x32_bf16 v[36:39], v[164:167], v[188:191], v[36:39]
	v_mfma_f32_16x16x32_bf16 v[32:35], v[172:175], v[188:191], v[32:35]
	v_mfma_f32_16x16x32_bf16 v[20:23], v[164:167], v[198:201], v[20:23]
	v_mfma_f32_16x16x32_bf16 v[16:19], v[172:175], v[198:201], v[16:19]
	v_mfma_f32_16x16x32_bf16 v[4:7], v[164:167], v[206:209], v[4:7]
	v_mfma_f32_16x16x32_bf16 v[0:3], v[172:175], v[206:209], v[0:3]
	s_barrier
	s_setprio 0
	s_add_i32 s65, 0, 0x18000
	s_add_i32 s66, 0, 0x1c000
	v_add_u32_e32 v156, s65, v143
	v_add_u32_e32 v172, s66, v143
	ds_read_b128 v[138:141], v156
	ds_read_b128 v[148:151], v156 offset:1024
	ds_read_b128 v[152:155], v156 offset:2048
	ds_read_b128 v[156:159], v156 offset:3072
	ds_read_b128 v[160:163], v172
	ds_read_b128 v[164:167], v172 offset:1024
	ds_read_b128 v[168:171], v172 offset:2048
	ds_read_b128 v[172:175], v172 offset:3072
	s_add_u32 s26, vcc_lo, 0x40000
	s_addc_u32 s27, vcc_hi, 0
	s_mov_b32 m0, s89
	v_lshl_add_u64 v[222:223], s[26:27], 0, v[128:129]
	ds_read_b128 v[176:179], v147 offset:32768
	ds_read_b128 v[180:183], v147 offset:33792
	ds_read_b128 v[184:187], v147 offset:34816
	ds_read_b128 v[188:191], v147 offset:35840
	ds_read_b128 v[194:197], v147 offset:36864
	ds_read_b128 v[198:201], v147 offset:37888
	ds_read_b128 v[202:205], v147 offset:38912
	ds_read_b128 v[206:209], v147 offset:39936
	global_load_lds_dwordx4 v[222:223], off
	v_lshl_add_u64 v[222:223], s[26:27], 0, v[130:131]
	s_mov_b32 m0, s90
	s_nop 0
	global_load_lds_dwordx4 v[222:223], off
	s_waitcnt vmcnt(8)
	s_waitcnt lgkmcnt(0)
	s_barrier
	s_setprio 1
	s_waitcnt lgkmcnt(0)
	v_mfma_f32_16x16x32_bf16 v[124:127], v[138:141], v[176:179], v[124:127]
	v_mfma_f32_16x16x32_bf16 v[120:123], v[152:155], v[176:179], v[120:123]
	v_mfma_f32_16x16x32_bf16 v[108:111], v[138:141], v[184:187], v[108:111]
	v_mfma_f32_16x16x32_bf16 v[104:107], v[152:155], v[184:187], v[104:107]
	v_mfma_f32_16x16x32_bf16 v[92:95], v[138:141], v[194:197], v[92:95]
	v_mfma_f32_16x16x32_bf16 v[88:91], v[152:155], v[194:197], v[88:91]
	v_mfma_f32_16x16x32_bf16 v[76:79], v[138:141], v[202:205], v[76:79]
	v_mfma_f32_16x16x32_bf16 v[72:75], v[152:155], v[202:205], v[72:75]
	v_mfma_f32_16x16x32_bf16 v[124:127], v[148:151], v[180:183], v[124:127]
	v_mfma_f32_16x16x32_bf16 v[120:123], v[156:159], v[180:183], v[120:123]
	v_mfma_f32_16x16x32_bf16 v[108:111], v[148:151], v[188:191], v[108:111]
	v_mfma_f32_16x16x32_bf16 v[104:107], v[156:159], v[188:191], v[104:107]
	v_mfma_f32_16x16x32_bf16 v[92:95], v[148:151], v[198:201], v[92:95]
	v_mfma_f32_16x16x32_bf16 v[88:91], v[156:159], v[198:201], v[88:91]
	v_mfma_f32_16x16x32_bf16 v[76:79], v[148:151], v[206:209], v[76:79]
	v_mfma_f32_16x16x32_bf16 v[72:75], v[156:159], v[206:209], v[72:75]
	s_setprio 0
	s_setprio 1
	v_mfma_f32_16x16x32_bf16 v[116:119], v[160:163], v[176:179], v[116:119]
	v_mfma_f32_16x16x32_bf16 v[112:115], v[168:171], v[176:179], v[112:115]
	v_mfma_f32_16x16x32_bf16 v[100:103], v[160:163], v[184:187], v[100:103]
	v_mfma_f32_16x16x32_bf16 v[96:99], v[168:171], v[184:187], v[96:99]
	v_mfma_f32_16x16x32_bf16 v[84:87], v[160:163], v[194:197], v[84:87]
	v_mfma_f32_16x16x32_bf16 v[80:83], v[168:171], v[194:197], v[80:83]
	v_mfma_f32_16x16x32_bf16 v[68:71], v[160:163], v[202:205], v[68:71]
	v_mfma_f32_16x16x32_bf16 v[64:67], v[168:171], v[202:205], v[64:67]
	v_mfma_f32_16x16x32_bf16 v[116:119], v[164:167], v[180:183], v[116:119]
	v_mfma_f32_16x16x32_bf16 v[112:115], v[172:175], v[180:183], v[112:115]
	v_mfma_f32_16x16x32_bf16 v[100:103], v[164:167], v[188:191], v[100:103]
	v_mfma_f32_16x16x32_bf16 v[96:99], v[172:175], v[188:191], v[96:99]
	v_mfma_f32_16x16x32_bf16 v[84:87], v[164:167], v[198:201], v[84:87]
	v_mfma_f32_16x16x32_bf16 v[80:83], v[172:175], v[198:201], v[80:83]
	v_mfma_f32_16x16x32_bf16 v[68:71], v[164:167], v[206:209], v[68:71]
	v_mfma_f32_16x16x32_bf16 v[64:67], v[172:175], v[206:209], v[64:67]
	s_barrier
; #define PG8_STAGE(bufoff, gbase, voff) do { _Pragma("unroll") for (int _i = 0; _i < 2; ++_i) \
;         __builtin_amdgcn_global_load_lds((const unsigned*)((const char*)(gbase) + (voff)[_i]), (PG8_LAS unsigned*)(lds + (bufoff) + ldsw + _i * 8192), 16, 0, 0); } while (0)
; #define PG8_LDA(dst, b, h) do { _Pragma("unroll") for (int m = 0; m < 4; ++m) _Pragma("unroll") for (int k = 0; k < 2; ++k) dst[m][k] = *(const PG8_LAS bf16x8*)(lds + PG8_SA(b, h) + aoff + m * 2048 + k * 1024); } while (0)
; #define PG8_MMA(ai, bj, At, Bt) do { __builtin_amdgcn_s_setprio(1); _Pragma("unroll") for (int m = 0; m < 4; ++m) _Pragma("unroll") for (int n = 0; n < 2; ++n) _Pragma("unroll") for (int k = 0; k < 2; ++k) \
;         acc[ai][bj][m][n] = __builtin_amdgcn_mfma_f32_16x16x32_bf16(Bt[n][k], At[m][k], acc[ai][bj][m][n], 0, 0, 0); __builtin_amdgcn_s_setprio(0); } while (0)
; #define PG8_WAIT_V(n) asm volatile("s_waitcnt vmcnt(" #n ")" ::: "memory")
; #define PG8_WAIT_L(n) asm volatile("s_waitcnt lgkmcnt(" #n ")" ::: "memory")
; #define PG8_BAR __builtin_amdgcn_s_barrier()
; #define PG8_SCHED __builtin_amdgcn_sched_barrier(0)
; template <class Epi, class Sched, bool ALIGN_EPI = false, bool SP2 = false>
; __device__ __forceinline__ void gemm_phase(PG8_LAS unsigned char* lds, const Gemm g, const Sched& S, const Epi& E, int wid0) {
;     ...
;             PG8_WAIT_V(8); PG8_WAIT_L(0); PG8_BAR; PG8_MMA(0, 0, At, B0); PG8_MMA(0, 1, At, B1); PG8_BAR; PG8_SCHED;
;             PG8_LDA(At, 1, 1); PG8_STAGE(PG8_SB(1, 0), b3, voffB); PG8_STAGE(PG8_SB(1, 1), b3 + hstep, voffB); PG8_STAGE(PG8_SA(1, 0), a3, voffA);
;             PG8_WAIT_V(8); PG8_WAIT_L(0); PG8_BAR; PG8_MMA(1, 0, At, B0); PG8_MMA(1, 1, At, B1); PG8_BAR; PG8_SCHED;
	s_setprio 0
	s_add_i32 s26, s65, s69
	v_lshl_add_u64 v[210:211], v[210:211], 0, s[30:31]
	s_mov_b32 m0, s26
	ds_read_b128 v[176:179], v147 offset:49152
	ds_read_b128 v[180:183], v147 offset:50176
	ds_read_b128 v[184:187], v147 offset:51200
	ds_read_b128 v[188:191], v147 offset:52224
	ds_read_b128 v[194:197], v147 offset:53248
	ds_read_b128 v[198:201], v147 offset:54272
	ds_read_b128 v[202:205], v147 offset:55296
	ds_read_b128 v[206:209], v147 offset:56320
	global_load_lds_dwordx4 v[210:211], off
	s_add_i32 m0, s26, 0x2000
	s_add_u32 s26, s76, 0x40080
	v_lshl_add_u64 v[210:211], v[212:213], 0, s[30:31]
	s_addc_u32 s27, s77, 0
	s_add_i32 s65, s66, s69
	global_load_lds_dwordx4 v[210:211], off
	v_lshl_add_u64 v[210:211], s[26:27], 0, v[192:193]
	s_mov_b32 m0, s65
	s_nop 0
	global_load_lds_dwordx4 v[210:211], off
	v_lshl_add_u64 v[210:211], s[26:27], 0, v[132:133]
	s_add_i32 m0, s65, 0x2000
	s_nop 0
	global_load_lds_dwordx4 v[210:211], off
	v_lshl_add_u64 v[210:211], v[214:215], 0, s[30:31]
	s_mov_b32 m0, s92
	s_nop 0
	global_load_lds_dwordx4 v[210:211], off
	v_lshl_add_u64 v[210:211], v[220:221], 0, s[30:31]
	s_mov_b32 m0, s93
	s_nop 0
	global_load_lds_dwordx4 v[210:211], off
	s_waitcnt vmcnt(8)
	s_waitcnt lgkmcnt(0)
	s_barrier
	s_setprio 1
	s_waitcnt lgkmcnt(0)
	v_mfma_f32_16x16x32_bf16 v[60:63], v[138:141], v[176:179], v[60:63]
	v_mfma_f32_16x16x32_bf16 v[56:59], v[152:155], v[176:179], v[56:59]
	v_mfma_f32_16x16x32_bf16 v[44:47], v[138:141], v[184:187], v[44:47]
	v_mfma_f32_16x16x32_bf16 v[40:43], v[152:155], v[184:187], v[40:43]
	v_mfma_f32_16x16x32_bf16 v[28:31], v[138:141], v[194:197], v[28:31]
	v_mfma_f32_16x16x32_bf16 v[24:27], v[152:155], v[194:197], v[24:27]
	v_mfma_f32_16x16x32_bf16 v[12:15], v[138:141], v[202:205], v[12:15]
	v_mfma_f32_16x16x32_bf16 v[8:11], v[152:155], v[202:205], v[8:11]
	v_mfma_f32_16x16x32_bf16 v[60:63], v[148:151], v[180:183], v[60:63]
	v_mfma_f32_16x16x32_bf16 v[56:59], v[156:159], v[180:183], v[56:59]
	v_mfma_f32_16x16x32_bf16 v[44:47], v[148:151], v[188:191], v[44:47]
	v_mfma_f32_16x16x32_bf16 v[40:43], v[156:159], v[188:191], v[40:43]
	v_mfma_f32_16x16x32_bf16 v[28:31], v[148:151], v[198:201], v[28:31]
	v_mfma_f32_16x16x32_bf16 v[24:27], v[156:159], v[198:201], v[24:27]
	v_mfma_f32_16x16x32_bf16 v[12:15], v[148:151], v[206:209], v[12:15]
	v_mfma_f32_16x16x32_bf16 v[8:11], v[156:159], v[206:209], v[8:11]
	s_setprio 0
	s_setprio 1
	v_mfma_f32_16x16x32_bf16 v[52:55], v[160:163], v[176:179], v[52:55]
	v_mfma_f32_16x16x32_bf16 v[48:51], v[168:171], v[176:179], v[48:51]
	v_mfma_f32_16x16x32_bf16 v[36:39], v[160:163], v[184:187], v[36:39]
	v_mfma_f32_16x16x32_bf16 v[32:35], v[168:171], v[184:187], v[32:35]
	v_mfma_f32_16x16x32_bf16 v[20:23], v[160:163], v[194:197], v[20:23]
	v_mfma_f32_16x16x32_bf16 v[16:19], v[168:171], v[194:197], v[16:19]
	v_mfma_f32_16x16x32_bf16 v[4:7], v[160:163], v[202:205], v[4:7]
	v_mfma_f32_16x16x32_bf16 v[0:3], v[168:171], v[202:205], v[0:3]
	v_mfma_f32_16x16x32_bf16 v[52:55], v[164:167], v[180:183], v[52:55]
	v_mfma_f32_16x16x32_bf16 v[48:51], v[172:175], v[180:183], v[48:51]
	v_mfma_f32_16x16x32_bf16 v[36:39], v[164:167], v[188:191], v[36:39]
	v_mfma_f32_16x16x32_bf16 v[32:35], v[172:175], v[188:191], v[32:35]
	v_mfma_f32_16x16x32_bf16 v[20:23], v[164:167], v[198:201], v[20:23]
	v_mfma_f32_16x16x32_bf16 v[16:19], v[172:175], v[198:201], v[16:19]
	v_mfma_f32_16x16x32_bf16 v[4:7], v[164:167], v[206:209], v[4:7]
	v_mfma_f32_16x16x32_bf16 v[0:3], v[172:175], v[206:209], v[0:3]
	s_barrier
	s_setprio 0
	s_add_i32 s64, s64, 2
	s_add_u32 s10, s10, 0x100
	s_addc_u32 s11, s11, 0
	s_add_u32 s84, s84, 0x100
	s_addc_u32 s85, s85, 0
	s_cmp_gt_u32 s64, 13
	s_cbranch_scc0 .LBB0_377
	s_and_b64 vcc, exec, s[70:71]
	s_cbranch_vccz .LBB0_380
	s_barrier

; #define PG8_STAGE(bufoff, gbase, voff) do { _Pragma("unroll") for (int _i = 0; _i < 2; ++_i) \
;         __builtin_amdgcn_global_load_lds((const unsigned*)((const char*)(gbase) + (voff)[_i]), (PG8_LAS unsigned*)(lds + (bufoff) + ldsw + _i * 8192), 16, 0, 0); } while (0)
; #define PG8_LDA(dst, b, h) do { _Pragma("unroll") for (int m = 0; m < 4; ++m) _Pragma("unroll") for (int k = 0; k < 2; ++k) dst[m][k] = *(const PG8_LAS bf16x8*)(lds + PG8_SA(b, h) + aoff + m * 2048 + k * 1024); } while (0)
; #define PG8_LDB(dst, b, h) do { _Pragma("unroll") for (int n = 0; n < 2; ++n) _Pragma("unroll") for (int k = 0; k < 2; ++k) dst[n][k] = *(const PG8_LAS bf16x8*)(lds + PG8_SB(b, h) + boff + n * 2048 + k * 1024); } while (0)
; #define PG8_MMA(ai, bj, At, Bt) do { __builtin_amdgcn_s_setprio(1); _Pragma("unroll") for (int m = 0; m < 4; ++m) _Pragma("unroll") for (int n = 0; n < 2; ++n) _Pragma("unroll") for (int k = 0; k < 2; ++k) \
;         acc[ai][bj][m][n] = __builtin_amdgcn_mfma_f32_16x16x32_bf16(Bt[n][k], At[m][k], acc[ai][bj][m][n], 0, 0, 0); __builtin_amdgcn_s_setprio(0); } while (0)
; #define PG8_WAIT_V(n) asm volatile("s_waitcnt vmcnt(" #n ")" ::: "memory")
; #define PG8_BAR __builtin_amdgcn_s_barrier()
; template <class Epi, class Sched, bool ALIGN_EPI = false, bool SP2 = false>
; __device__ __forceinline__ void gemm_phase(PG8_LAS unsigned char* lds, const Gemm g, const Sched& S, const Epi& E, int wid0) {
;     ...
;         for (int t = 0; t < nt; t += 2) {
;             const bool last = (t == nt - 2);
;             const char* a1 = cA + (size_t)(t + 1) * kstep;
;             const char* a2 = last ? nA : cA + (size_t)(t + 2) * kstep; const char* b2 = last ? nB : cB + (size_t)(t + 2) * kstep;
;             const char* a3 = a2 + kstep; const char* b3 = b2 + kstep;
;             if (last && has_next) S.a_ready(nxt);
;             if constexpr (SP2) {
;             PG8_LDB(B0, 0, 0); PG8_LDB(B1, 0, 1); PG8_SCHED; PG8_LDA(At, 0, 0); PG8_STAGE(PG8_SA(1, 1), a1 + hstep, voffA);
;             PG8_WAIT_V(8); PG8_WAIT_L(0); PG8_BAR; PG8_MMA(0, 0, At, B0); PG8_MMA(0, 1, At, B1); PG8_BAR; PG8_SCHED;
;             PG8_LDA(At, 0, 1); PG8_STAGE(PG8_SB(0, 0), b2, voffB); PG8_STAGE(PG8_SB(0, 1), b2 + hstep, voffB); PG8_STAGE(PG8_SA(0, 0), a2, voffA);
;             PG8_WAIT_V(8); PG8_WAIT_L(0); PG8_BAR; PG8_MMA(1, 0, At, B0); PG8_MMA(1, 1, At, B1); PG8_BAR; PG8_SCHED;
.LBB0_544:
	s_add_i32 s65, 0, 0x10000
	v_add_u32_e32 v142, s65, v146
	s_add_i32 s66, 0, 0x14000
	ds_read_b128 v[138:141], v142
	ds_read_b128 v[150:153], v142 offset:1024
	ds_read_b128 v[154:157], v142 offset:2048
	ds_read_b128 v[158:161], v142 offset:3072
	v_add_u32_e32 v142, s66, v146
	ds_read_b128 v[162:165], v142
	ds_read_b128 v[166:169], v142 offset:1024
	ds_read_b128 v[170:173], v142 offset:2048
	ds_read_b128 v[174:177], v142 offset:3072
	v_lshl_add_u64 v[142:143], s[80:81], 0, v[136:137]
	s_add_i32 m0, s87, 0xc000
	ds_read_b128 v[178:181], v148
	ds_read_b128 v[182:185], v148 offset:1024
	ds_read_b128 v[186:189], v148 offset:2048
	ds_read_b128 v[194:197], v148 offset:3072
	ds_read_b128 v[198:201], v148 offset:4096
	ds_read_b128 v[202:205], v148 offset:5120
	ds_read_b128 v[206:209], v148 offset:6144
	ds_read_b128 v[210:213], v148 offset:7168
	global_load_lds_dwordx4 v[142:143], off
	v_lshl_add_u64 v[142:143], s[80:81], 0, v[134:135]
	s_add_i32 m0, s87, 0xe000
	s_nop 0
	global_load_lds_dwordx4 v[142:143], off
	s_add_u32 s26, s80, 0xfffc0080
	s_addc_u32 s27, s81, -1
	s_cmp_eq_u32 s64, 12
	s_cselect_b32 s85, s45, s27
	s_cselect_b32 s84, s73, s26
	s_cselect_b32 s83, s71, s11
	s_cselect_b32 s82, s79, s10
	s_waitcnt vmcnt(8)
	s_waitcnt lgkmcnt(0)
	s_barrier
	s_setprio 1
	s_waitcnt lgkmcnt(0)
	v_mfma_f32_16x16x32_bf16 v[124:127], v[138:141], v[178:181], v[124:127]
	v_mfma_f32_16x16x32_bf16 v[116:119], v[154:157], v[178:181], v[116:119]
	v_mfma_f32_16x16x32_bf16 v[108:111], v[138:141], v[186:189], v[108:111]
	v_mfma_f32_16x16x32_bf16 v[100:103], v[154:157], v[186:189], v[100:103]
	v_mfma_f32_16x16x32_bf16 v[92:95], v[138:141], v[198:201], v[92:95]
	v_mfma_f32_16x16x32_bf16 v[84:87], v[154:157], v[198:201], v[84:87]
	v_mfma_f32_16x16x32_bf16 v[76:79], v[138:141], v[206:209], v[76:79]
	v_mfma_f32_16x16x32_bf16 v[68:71], v[154:157], v[206:209], v[68:71]
	v_mfma_f32_16x16x32_bf16 v[124:127], v[150:153], v[182:185], v[124:127]
	v_mfma_f32_16x16x32_bf16 v[116:119], v[158:161], v[182:185], v[116:119]
	v_mfma_f32_16x16x32_bf16 v[108:111], v[150:153], v[194:197], v[108:111]
	v_mfma_f32_16x16x32_bf16 v[100:103], v[158:161], v[194:197], v[100:103]
	v_mfma_f32_16x16x32_bf16 v[92:95], v[150:153], v[202:205], v[92:95]
	v_mfma_f32_16x16x32_bf16 v[84:87], v[158:161], v[202:205], v[84:87]
	v_mfma_f32_16x16x32_bf16 v[76:79], v[150:153], v[210:213], v[76:79]
	v_mfma_f32_16x16x32_bf16 v[68:71], v[158:161], v[210:213], v[68:71]
	s_setprio 0
	s_setprio 1
	v_mfma_f32_16x16x32_bf16 v[120:123], v[162:165], v[178:181], v[120:123]
	v_mfma_f32_16x16x32_bf16 v[112:115], v[170:173], v[178:181], v[112:115]
	v_mfma_f32_16x16x32_bf16 v[104:107], v[162:165], v[186:189], v[104:107]
	v_mfma_f32_16x16x32_bf16 v[96:99], v[170:173], v[186:189], v[96:99]
	v_mfma_f32_16x16x32_bf16 v[88:91], v[162:165], v[198:201], v[88:91]
	v_mfma_f32_16x16x32_bf16 v[80:83], v[170:173], v[198:201], v[80:83]
	v_mfma_f32_16x16x32_bf16 v[72:75], v[162:165], v[206:209], v[72:75]
	v_mfma_f32_16x16x32_bf16 v[64:67], v[170:173], v[206:209], v[64:67]
	v_mfma_f32_16x16x32_bf16 v[120:123], v[166:169], v[182:185], v[120:123]
	v_mfma_f32_16x16x32_bf16 v[112:115], v[174:177], v[182:185], v[112:115]
	v_mfma_f32_16x16x32_bf16 v[104:107], v[166:169], v[194:197], v[104:107]
	v_mfma_f32_16x16x32_bf16 v[96:99], v[174:177], v[194:197], v[96:99]
	v_mfma_f32_16x16x32_bf16 v[88:91], v[166:169], v[202:205], v[88:91]
	v_mfma_f32_16x16x32_bf16 v[80:83], v[174:177], v[202:205], v[80:83]
	v_mfma_f32_16x16x32_bf16 v[72:75], v[166:169], v[210:213], v[72:75]
	v_mfma_f32_16x16x32_bf16 v[64:67], v[174:177], v[210:213], v[64:67]
	s_barrier
	s_setprio 0
	s_add_i32 s26, s65, s86
	v_lshl_add_u64 v[142:143], s[82:83], 0, v[192:193]
	s_mov_b32 m0, s26
	ds_read_b128 v[178:181], v148 offset:16384
	ds_read_b128 v[182:185], v148 offset:17408
	ds_read_b128 v[186:189], v148 offset:18432
	ds_read_b128 v[194:197], v148 offset:19456
	ds_read_b128 v[198:201], v148 offset:20480
	ds_read_b128 v[202:205], v148 offset:21504
	ds_read_b128 v[206:209], v148 offset:22528
	ds_read_b128 v[210:213], v148 offset:23552
	global_load_lds_dwordx4 v[142:143], off
	s_add_i32 m0, s26, 0x2000
	s_add_u32 s26, s82, 0x40000
	v_lshl_add_u64 v[190:191], s[82:83], 0, v[128:129]
	s_addc_u32 s27, s83, 0
	s_add_i32 s65, s66, s86
	global_load_lds_dwordx4 v[190:191], off
	v_lshl_add_u64 v[214:215], s[26:27], 0, v[192:193]
	s_mov_b32 m0, s65
	v_lshl_add_u64 v[220:221], s[84:85], 0, v[130:131]
	global_load_lds_dwordx4 v[214:215], off
	v_lshl_add_u64 v[214:215], s[26:27], 0, v[128:129]
	s_add_i32 m0, s65, 0x2000
	s_nop 0
	global_load_lds_dwordx4 v[214:215], off
	v_lshl_add_u64 v[214:215], s[84:85], 0, v[132:133]
	s_mov_b32 m0, s87
	s_nop 0
	global_load_lds_dwordx4 v[214:215], off
	s_mov_b32 m0, s88
	s_nop 0
	global_load_lds_dwordx4 v[220:221], off
	s_waitcnt vmcnt(8)
	s_waitcnt lgkmcnt(0)
	s_barrier
; #define PG8_STAGE(bufoff, gbase, voff) do { _Pragma("unroll") for (int _i = 0; _i < 2; ++_i) \
;         __builtin_amdgcn_global_load_lds((const unsigned*)((const char*)(gbase) + (voff)[_i]), (PG8_LAS unsigned*)(lds + (bufoff) + ldsw + _i * 8192), 16, 0, 0); } while (0)
; #define PG8_LDA(dst, b, h) do { _Pragma("unroll") for (int m = 0; m < 4; ++m) _Pragma("unroll") for (int k = 0; k < 2; ++k) dst[m][k] = *(const PG8_LAS bf16x8*)(lds + PG8_SA(b, h) + aoff + m * 2048 + k * 1024); } while (0)
; #define PG8_LDB(dst, b, h) do { _Pragma("unroll") for (int n = 0; n < 2; ++n) _Pragma("unroll") for (int k = 0; k < 2; ++k) dst[n][k] = *(const PG8_LAS bf16x8*)(lds + PG8_SB(b, h) + boff + n * 2048 + k * 1024); } while (0)
; #define PG8_MMA(ai, bj, At, Bt) do { __builtin_amdgcn_s_setprio(1); _Pragma("unroll") for (int m = 0; m < 4; ++m) _Pragma("unroll") for (int n = 0; n < 2; ++n) _Pragma("unroll") for (int k = 0; k < 2; ++k) \
;         acc[ai][bj][m][n] = __builtin_amdgcn_mfma_f32_16x16x32_bf16(Bt[n][k], At[m][k], acc[ai][bj][m][n], 0, 0, 0); __builtin_amdgcn_s_setprio(0); } while (0)
; #define PG8_WAIT_V(n) asm volatile("s_waitcnt vmcnt(" #n ")" ::: "memory")
; #define PG8_WAIT_L(n) asm volatile("s_waitcnt lgkmcnt(" #n ")" ::: "memory")
; #define PG8_BAR __builtin_amdgcn_s_barrier()
; #define PG8_SCHED __builtin_amdgcn_sched_barrier(0)
; template <class Epi, class Sched, bool ALIGN_EPI = false, bool SP2 = false>
; __device__ __forceinline__ void gemm_phase(PG8_LAS unsigned char* lds, const Gemm g, const Sched& S, const Epi& E, int wid0) {
;     ...
;             PG8_WAIT_V(8); PG8_WAIT_L(0); PG8_BAR; PG8_MMA(1, 0, At, B0); PG8_MMA(1, 1, At, B1); PG8_BAR; PG8_SCHED;
;             PG8_LDB(B0, 1, 0); PG8_LDB(B1, 1, 1); PG8_SCHED; PG8_LDA(At, 1, 0); PG8_STAGE(PG8_SA(0, 1), a2 + hstep, voffA);
;             PG8_WAIT_V(8); PG8_WAIT_L(0); PG8_BAR; PG8_MMA(0, 0, At, B0); PG8_MMA(0, 1, At, B1); PG8_BAR; PG8_SCHED;
;             PG8_LDA(At, 1, 1); PG8_STAGE(PG8_SB(1, 0), b3, voffB); PG8_STAGE(PG8_SB(1, 1), b3 + hstep, voffB); PG8_STAGE(PG8_SA(1, 0), a3, voffA);
	s_setprio 1
	s_waitcnt lgkmcnt(0)
	v_mfma_f32_16x16x32_bf16 v[60:63], v[138:141], v[178:181], v[60:63]
	v_mfma_f32_16x16x32_bf16 v[52:55], v[154:157], v[178:181], v[52:55]
	v_mfma_f32_16x16x32_bf16 v[44:47], v[138:141], v[186:189], v[44:47]
	v_mfma_f32_16x16x32_bf16 v[36:39], v[154:157], v[186:189], v[36:39]
	v_mfma_f32_16x16x32_bf16 v[28:31], v[138:141], v[198:201], v[28:31]
	v_mfma_f32_16x16x32_bf16 v[20:23], v[154:157], v[198:201], v[20:23]
	v_mfma_f32_16x16x32_bf16 v[12:15], v[138:141], v[206:209], v[12:15]
	v_mfma_f32_16x16x32_bf16 v[4:7], v[154:157], v[206:209], v[4:7]
	v_mfma_f32_16x16x32_bf16 v[60:63], v[150:153], v[182:185], v[60:63]
	v_mfma_f32_16x16x32_bf16 v[52:55], v[158:161], v[182:185], v[52:55]
	v_mfma_f32_16x16x32_bf16 v[44:47], v[150:153], v[194:197], v[44:47]
	v_mfma_f32_16x16x32_bf16 v[36:39], v[158:161], v[194:197], v[36:39]
	v_mfma_f32_16x16x32_bf16 v[28:31], v[150:153], v[202:205], v[28:31]
	v_mfma_f32_16x16x32_bf16 v[20:23], v[158:161], v[202:205], v[20:23]
	v_mfma_f32_16x16x32_bf16 v[12:15], v[150:153], v[210:213], v[12:15]
	v_mfma_f32_16x16x32_bf16 v[4:7], v[158:161], v[210:213], v[4:7]
	s_setprio 0
	s_setprio 1
	v_mfma_f32_16x16x32_bf16 v[56:59], v[162:165], v[178:181], v[56:59]
	v_mfma_f32_16x16x32_bf16 v[48:51], v[170:173], v[178:181], v[48:51]
	v_mfma_f32_16x16x32_bf16 v[40:43], v[162:165], v[186:189], v[40:43]
	v_mfma_f32_16x16x32_bf16 v[32:35], v[170:173], v[186:189], v[32:35]
	v_mfma_f32_16x16x32_bf16 v[24:27], v[162:165], v[198:201], v[24:27]
	v_mfma_f32_16x16x32_bf16 v[16:19], v[170:173], v[198:201], v[16:19]
	v_mfma_f32_16x16x32_bf16 v[8:11], v[162:165], v[206:209], v[8:11]
	v_mfma_f32_16x16x32_bf16 v[0:3], v[170:173], v[206:209], v[0:3]
	v_mfma_f32_16x16x32_bf16 v[56:59], v[166:169], v[182:185], v[56:59]
	v_mfma_f32_16x16x32_bf16 v[48:51], v[174:177], v[182:185], v[48:51]
	v_mfma_f32_16x16x32_bf16 v[40:43], v[166:169], v[194:197], v[40:43]
	v_mfma_f32_16x16x32_bf16 v[32:35], v[174:177], v[194:197], v[32:35]
	v_mfma_f32_16x16x32_bf16 v[24:27], v[166:169], v[202:205], v[24:27]
	v_mfma_f32_16x16x32_bf16 v[16:19], v[174:177], v[202:205], v[16:19]
	v_mfma_f32_16x16x32_bf16 v[8:11], v[166:169], v[210:213], v[8:11]
	v_mfma_f32_16x16x32_bf16 v[0:3], v[174:177], v[210:213], v[0:3]
	s_barrier
	s_setprio 0
	s_add_i32 s65, 0, 0x18000
	v_add_u32_e32 v144, s65, v146
	s_add_i32 s66, 0, 0x1c000
	ds_read_b128 v[138:141], v144
	ds_read_b128 v[150:153], v144 offset:1024
	ds_read_b128 v[154:157], v144 offset:2048
	ds_read_b128 v[158:161], v144 offset:3072
	v_add_u32_e32 v144, s66, v146
	ds_read_b128 v[162:165], v144
	ds_read_b128 v[166:169], v144 offset:1024
	ds_read_b128 v[170:173], v144 offset:2048
	ds_read_b128 v[174:177], v144 offset:3072
	s_add_u32 s26, s84, 0x40000
	s_addc_u32 s27, s85, 0
	s_mov_b32 m0, s89
	v_lshl_add_u64 v[222:223], s[26:27], 0, v[132:133]
	ds_read_b128 v[178:181], v148 offset:32768
	ds_read_b128 v[182:185], v148 offset:33792
	ds_read_b128 v[186:189], v148 offset:34816
	ds_read_b128 v[194:197], v148 offset:35840
	ds_read_b128 v[198:201], v148 offset:36864
	ds_read_b128 v[202:205], v148 offset:37888
	ds_read_b128 v[206:209], v148 offset:38912
	ds_read_b128 v[210:213], v148 offset:39936
	global_load_lds_dwordx4 v[222:223], off
	v_lshl_add_u64 v[222:223], s[26:27], 0, v[130:131]
	s_mov_b32 m0, s90
	s_nop 0
	global_load_lds_dwordx4 v[222:223], off
	s_waitcnt vmcnt(8)
	s_waitcnt lgkmcnt(0)
	s_barrier
	s_setprio 1
	s_waitcnt lgkmcnt(0)
	v_mfma_f32_16x16x32_bf16 v[124:127], v[138:141], v[178:181], v[124:127]
	v_mfma_f32_16x16x32_bf16 v[116:119], v[154:157], v[178:181], v[116:119]
	v_mfma_f32_16x16x32_bf16 v[108:111], v[138:141], v[186:189], v[108:111]
	v_mfma_f32_16x16x32_bf16 v[100:103], v[154:157], v[186:189], v[100:103]
	v_mfma_f32_16x16x32_bf16 v[92:95], v[138:141], v[198:201], v[92:95]
	v_mfma_f32_16x16x32_bf16 v[84:87], v[154:157], v[198:201], v[84:87]
	v_mfma_f32_16x16x32_bf16 v[76:79], v[138:141], v[206:209], v[76:79]
	v_mfma_f32_16x16x32_bf16 v[68:71], v[154:157], v[206:209], v[68:71]
	v_mfma_f32_16x16x32_bf16 v[124:127], v[150:153], v[182:185], v[124:127]
	v_mfma_f32_16x16x32_bf16 v[116:119], v[158:161], v[182:185], v[116:119]
	v_mfma_f32_16x16x32_bf16 v[108:111], v[150:153], v[194:197], v[108:111]
	v_mfma_f32_16x16x32_bf16 v[100:103], v[158:161], v[194:197], v[100:103]
	v_mfma_f32_16x16x32_bf16 v[92:95], v[150:153], v[202:205], v[92:95]
	v_mfma_f32_16x16x32_bf16 v[84:87], v[158:161], v[202:205], v[84:87]
	v_mfma_f32_16x16x32_bf16 v[76:79], v[150:153], v[210:213], v[76:79]
	v_mfma_f32_16x16x32_bf16 v[68:71], v[158:161], v[210:213], v[68:71]
	s_setprio 0
	s_setprio 1
	v_mfma_f32_16x16x32_bf16 v[120:123], v[162:165], v[178:181], v[120:123]
	v_mfma_f32_16x16x32_bf16 v[112:115], v[170:173], v[178:181], v[112:115]
	v_mfma_f32_16x16x32_bf16 v[104:107], v[162:165], v[186:189], v[104:107]
	v_mfma_f32_16x16x32_bf16 v[96:99], v[170:173], v[186:189], v[96:99]
	v_mfma_f32_16x16x32_bf16 v[88:91], v[162:165], v[198:201], v[88:91]
	v_mfma_f32_16x16x32_bf16 v[80:83], v[170:173], v[198:201], v[80:83]
	v_mfma_f32_16x16x32_bf16 v[72:75], v[162:165], v[206:209], v[72:75]
	v_mfma_f32_16x16x32_bf16 v[64:67], v[170:173], v[206:209], v[64:67]
	v_mfma_f32_16x16x32_bf16 v[120:123], v[166:169], v[182:185], v[120:123]
	v_mfma_f32_16x16x32_bf16 v[112:115], v[174:177], v[182:185], v[112:115]
	v_mfma_f32_16x16x32_bf16 v[104:107], v[166:169], v[194:197], v[104:107]
	v_mfma_f32_16x16x32_bf16 v[96:99], v[174:177], v[194:197], v[96:99]
	v_mfma_f32_16x16x32_bf16 v[88:91], v[166:169], v[202:205], v[88:91]
	v_mfma_f32_16x16x32_bf16 v[80:83], v[174:177], v[202:205], v[80:83]
	v_mfma_f32_16x16x32_bf16 v[72:75], v[166:169], v[210:213], v[72:75]
	v_mfma_f32_16x16x32_bf16 v[64:67], v[174:177], v[210:213], v[64:67]
	s_barrier
; #define PG8_STAGE(bufoff, gbase, voff) do { _Pragma("unroll") for (int _i = 0; _i < 2; ++_i) \
;         __builtin_amdgcn_global_load_lds((const unsigned*)((const char*)(gbase) + (voff)[_i]), (PG8_LAS unsigned*)(lds + (bufoff) + ldsw + _i * 8192), 16, 0, 0); } while (0)
; #define PG8_LDA(dst, b, h) do { _Pragma("unroll") for (int m = 0; m < 4; ++m) _Pragma("unroll") for (int k = 0; k < 2; ++k) dst[m][k] = *(const PG8_LAS bf16x8*)(lds + PG8_SA(b, h) + aoff + m * 2048 + k * 1024); } while (0)
; #define PG8_MMA(ai, bj, At, Bt) do { __builtin_amdgcn_s_setprio(1); _Pragma("unroll") for (int m = 0; m < 4; ++m) _Pragma("unroll") for (int n = 0; n < 2; ++n) _Pragma("unroll") for (int k = 0; k < 2; ++k) \
;         acc[ai][bj][m][n] = __builtin_amdgcn_mfma_f32_16x16x32_bf16(Bt[n][k], At[m][k], acc[ai][bj][m][n], 0, 0, 0); __builtin_amdgcn_s_setprio(0); } while (0)
; #define PG8_WAIT_V(n) asm volatile("s_waitcnt vmcnt(" #n ")" ::: "memory")
; #define PG8_WAIT_L(n) asm volatile("s_waitcnt lgkmcnt(" #n ")" ::: "memory")
; #define PG8_BAR __builtin_amdgcn_s_barrier()
; #define PG8_SCHED __builtin_amdgcn_sched_barrier(0)
; template <class Epi, class Sched, bool ALIGN_EPI = false, bool SP2 = false>
; __device__ __forceinline__ void gemm_phase(PG8_LAS unsigned char* lds, const Gemm g, const Sched& S, const Epi& E, int wid0) {
;     ...
;             PG8_WAIT_V(8); PG8_WAIT_L(0); PG8_BAR; PG8_MMA(0, 0, At, B0); PG8_MMA(0, 1, At, B1); PG8_BAR; PG8_SCHED;
;             PG8_LDA(At, 1, 1); PG8_STAGE(PG8_SB(1, 0), b3, voffB); PG8_STAGE(PG8_SB(1, 1), b3 + hstep, voffB); PG8_STAGE(PG8_SA(1, 0), a3, voffA);
;             PG8_WAIT_V(8); PG8_WAIT_L(0); PG8_BAR; PG8_MMA(1, 0, At, B0); PG8_MMA(1, 1, At, B1); PG8_BAR; PG8_SCHED;
	s_setprio 0
	s_add_i32 s26, s65, s86
	v_lshl_add_u64 v[142:143], v[142:143], 0, s[30:31]
	s_mov_b32 m0, s26
	ds_read_b128 v[178:181], v148 offset:49152
	ds_read_b128 v[182:185], v148 offset:50176
	ds_read_b128 v[186:189], v148 offset:51200
	ds_read_b128 v[194:197], v148 offset:52224
	ds_read_b128 v[198:201], v148 offset:53248
	ds_read_b128 v[202:205], v148 offset:54272
	ds_read_b128 v[206:209], v148 offset:55296
	ds_read_b128 v[210:213], v148 offset:56320
	global_load_lds_dwordx4 v[142:143], off
	s_add_i32 m0, s26, 0x2000
	s_add_u32 s26, s82, 0x40080
	v_lshl_add_u64 v[142:143], v[190:191], 0, s[30:31]
	s_addc_u32 s27, s83, 0
	s_add_i32 s65, s66, s86
	global_load_lds_dwordx4 v[142:143], off
	v_lshl_add_u64 v[142:143], s[26:27], 0, v[192:193]
	s_mov_b32 m0, s65
	s_nop 0
	global_load_lds_dwordx4 v[142:143], off
	v_lshl_add_u64 v[142:143], s[26:27], 0, v[128:129]
	s_add_i32 m0, s65, 0x2000
	s_nop 0
	global_load_lds_dwordx4 v[142:143], off
	v_lshl_add_u64 v[142:143], v[214:215], 0, s[30:31]
	s_mov_b32 m0, s91
	s_nop 0
	global_load_lds_dwordx4 v[142:143], off
	v_lshl_add_u64 v[142:143], v[220:221], 0, s[30:31]
	s_mov_b32 m0, s92
	s_nop 0
	global_load_lds_dwordx4 v[142:143], off
	s_waitcnt vmcnt(8)
	s_waitcnt lgkmcnt(0)
	s_barrier
	s_setprio 1
	s_waitcnt lgkmcnt(0)
	v_mfma_f32_16x16x32_bf16 v[60:63], v[138:141], v[178:181], v[60:63]
	v_mfma_f32_16x16x32_bf16 v[52:55], v[154:157], v[178:181], v[52:55]
	v_mfma_f32_16x16x32_bf16 v[44:47], v[138:141], v[186:189], v[44:47]
	v_mfma_f32_16x16x32_bf16 v[36:39], v[154:157], v[186:189], v[36:39]
	v_mfma_f32_16x16x32_bf16 v[28:31], v[138:141], v[198:201], v[28:31]
	v_mfma_f32_16x16x32_bf16 v[20:23], v[154:157], v[198:201], v[20:23]
	v_mfma_f32_16x16x32_bf16 v[12:15], v[138:141], v[206:209], v[12:15]
	v_mfma_f32_16x16x32_bf16 v[4:7], v[154:157], v[206:209], v[4:7]
	v_mfma_f32_16x16x32_bf16 v[60:63], v[150:153], v[182:185], v[60:63]
	v_mfma_f32_16x16x32_bf16 v[52:55], v[158:161], v[182:185], v[52:55]
	v_mfma_f32_16x16x32_bf16 v[44:47], v[150:153], v[194:197], v[44:47]
	v_mfma_f32_16x16x32_bf16 v[36:39], v[158:161], v[194:197], v[36:39]
	v_mfma_f32_16x16x32_bf16 v[28:31], v[150:153], v[202:205], v[28:31]
	v_mfma_f32_16x16x32_bf16 v[20:23], v[158:161], v[202:205], v[20:23]
	v_mfma_f32_16x16x32_bf16 v[12:15], v[150:153], v[210:213], v[12:15]
	v_mfma_f32_16x16x32_bf16 v[4:7], v[158:161], v[210:213], v[4:7]
	s_setprio 0
	s_setprio 1
	v_mfma_f32_16x16x32_bf16 v[56:59], v[162:165], v[178:181], v[56:59]
	v_mfma_f32_16x16x32_bf16 v[48:51], v[170:173], v[178:181], v[48:51]
	v_mfma_f32_16x16x32_bf16 v[40:43], v[162:165], v[186:189], v[40:43]
	v_mfma_f32_16x16x32_bf16 v[32:35], v[170:173], v[186:189], v[32:35]
	v_mfma_f32_16x16x32_bf16 v[24:27], v[162:165], v[198:201], v[24:27]
	v_mfma_f32_16x16x32_bf16 v[16:19], v[170:173], v[198:201], v[16:19]
	v_mfma_f32_16x16x32_bf16 v[8:11], v[162:165], v[206:209], v[8:11]
	v_mfma_f32_16x16x32_bf16 v[0:3], v[170:173], v[206:209], v[0:3]
	v_mfma_f32_16x16x32_bf16 v[56:59], v[166:169], v[182:185], v[56:59]
	v_mfma_f32_16x16x32_bf16 v[48:51], v[174:177], v[182:185], v[48:51]
	v_mfma_f32_16x16x32_bf16 v[40:43], v[166:169], v[194:197], v[40:43]
	v_mfma_f32_16x16x32_bf16 v[32:35], v[174:177], v[194:197], v[32:35]
	v_mfma_f32_16x16x32_bf16 v[24:27], v[166:169], v[202:205], v[24:27]
	v_mfma_f32_16x16x32_bf16 v[16:19], v[174:177], v[202:205], v[16:19]
	v_mfma_f32_16x16x32_bf16 v[8:11], v[166:169], v[210:213], v[8:11]
	v_mfma_f32_16x16x32_bf16 v[0:3], v[174:177], v[210:213], v[0:3]
	s_barrier
	s_setprio 0
	s_add_i32 s64, s64, 2
	s_add_u32 s10, s10, 0x100
	s_addc_u32 s11, s11, 0
	s_add_u32 s80, s80, 0x100
	s_addc_u32 s81, s81, 0
	s_cmp_gt_u32 s64, 13
	s_cbranch_scc0 .LBB0_544
	s_and_b64 vcc, exec, s[42:43]
	s_cbranch_vccz .LBB0_547
	s_barrier

; #define PG8_STAGE(bufoff, gbase, voff) do { _Pragma("unroll") for (int _i = 0; _i < 2; ++_i) \
;         __builtin_amdgcn_global_load_lds((const unsigned*)((const char*)(gbase) + (voff)[_i]), (PG8_LAS unsigned*)(lds + (bufoff) + ldsw + _i * 8192), 16, 0, 0); } while (0)
; #define PG8_LDA(dst, b, h) do { _Pragma("unroll") for (int m = 0; m < 4; ++m) _Pragma("unroll") for (int k = 0; k < 2; ++k) dst[m][k] = *(const PG8_LAS bf16x8*)(lds + PG8_SA(b, h) + aoff + m * 2048 + k * 1024); } while (0)
; #define PG8_LDB(dst, b, h) do { _Pragma("unroll") for (int n = 0; n < 2; ++n) _Pragma("unroll") for (int k = 0; k < 2; ++k) dst[n][k] = *(const PG8_LAS bf16x8*)(lds + PG8_SB(b, h) + boff + n * 2048 + k * 1024); } while (0)
; #define PG8_MMA(ai, bj, At, Bt) do { __builtin_amdgcn_s_setprio(1); _Pragma("unroll") for (int m = 0; m < 4; ++m) _Pragma("unroll") for (int n = 0; n < 2; ++n) _Pragma("unroll") for (int k = 0; k < 2; ++k) \
;         acc[ai][bj][m][n] = __builtin_amdgcn_mfma_f32_16x16x32_bf16(Bt[n][k], At[m][k], acc[ai][bj][m][n], 0, 0, 0); __builtin_amdgcn_s_setprio(0); } while (0)
; #define PG8_WAIT_V(n) asm volatile("s_waitcnt vmcnt(" #n ")" ::: "memory")
; #define PG8_WAIT_L(n) asm volatile("s_waitcnt lgkmcnt(" #n ")" ::: "memory")
; template <class Epi, class Sched, bool ALIGN_EPI = false, bool SP2 = false>
; __device__ __forceinline__ void gemm_phase(PG8_LAS unsigned char* lds, const Gemm g, const Sched& S, const Epi& E, int wid0) {
;     ...
;             const bool last = (t == nt - 2);
;             const char* a1 = cA + (size_t)(t + 1) * kstep;
;             const char* a2 = last ? nA : cA + (size_t)(t + 2) * kstep; const char* b2 = last ? nB : cB + (size_t)(t + 2) * kstep;
;             const char* a3 = a2 + kstep; const char* b3 = b2 + kstep;
;             if (last && has_next) S.a_ready(nxt);
;             if constexpr (SP2) {
;             PG8_LDB(B0, 0, 0); PG8_LDB(B1, 0, 1); PG8_SCHED; PG8_LDA(At, 0, 0); PG8_STAGE(PG8_SA(1, 1), a1 + hstep, voffA);
;             PG8_WAIT_V(8); PG8_WAIT_L(0); PG8_BAR; PG8_MMA(0, 0, At, B0); PG8_MMA(0, 1, At, B1); PG8_BAR; PG8_SCHED;
;             PG8_LDA(At, 0, 1); PG8_STAGE(PG8_SB(0, 0), b2, voffB); PG8_STAGE(PG8_SB(0, 1), b2 + hstep, voffB); PG8_STAGE(PG8_SA(0, 0), a2, voffA);
;             PG8_WAIT_V(8); PG8_WAIT_L(0); PG8_BAR; PG8_MMA(1, 0, At, B0); PG8_MMA(1, 1, At, B1); PG8_BAR; PG8_SCHED;
.LBB0_630:
	s_add_i32 s26, 0, 0x10000
	s_add_i32 s65, 0, 0x14000
	v_add_u32_e32 v156, s26, v143
	v_add_u32_e32 v172, s65, v143
	ds_read_b128 v[138:141], v156
	ds_read_b128 v[148:151], v156 offset:1024
	ds_read_b128 v[152:155], v156 offset:2048
	ds_read_b128 v[156:159], v156 offset:3072
	ds_read_b128 v[160:163], v172
	ds_read_b128 v[164:167], v172 offset:1024
	ds_read_b128 v[168:171], v172 offset:2048
	ds_read_b128 v[172:175], v172 offset:3072
	v_lshl_add_u64 v[210:211], s[76:77], 0, v[136:137]
	s_add_i32 m0, s84, 0xc000
	ds_read_b128 v[176:179], v147
	ds_read_b128 v[180:183], v147 offset:1024
	ds_read_b128 v[184:187], v147 offset:2048
	ds_read_b128 v[188:191], v147 offset:3072
	ds_read_b128 v[194:197], v147 offset:4096
	ds_read_b128 v[198:201], v147 offset:5120
	ds_read_b128 v[202:205], v147 offset:6144
	ds_read_b128 v[206:209], v147 offset:7168
	global_load_lds_dwordx4 v[210:211], off
	v_lshl_add_u64 v[210:211], s[76:77], 0, v[134:135]
	s_add_i32 m0, s84, 0xe000
	s_nop 0
	global_load_lds_dwordx4 v[210:211], off
	s_add_u32 s78, s76, 0x100
	s_addc_u32 s79, s77, 0
	s_cmp_eq_u32 s64, 40
	s_cselect_b32 s83, s43, s79
	s_cselect_b32 s82, s42, s78
	s_cselect_b32 s81, s75, s11
	s_cselect_b32 s80, s74, s10
	s_waitcnt vmcnt(8)
	s_waitcnt lgkmcnt(0)
	s_barrier
	s_setprio 1
	s_waitcnt lgkmcnt(0)
	v_mfma_f32_16x16x32_bf16 v[124:127], v[138:141], v[176:179], v[124:127]
	v_mfma_f32_16x16x32_bf16 v[120:123], v[152:155], v[176:179], v[120:123]
	v_mfma_f32_16x16x32_bf16 v[108:111], v[138:141], v[184:187], v[108:111]
	v_mfma_f32_16x16x32_bf16 v[104:107], v[152:155], v[184:187], v[104:107]
	v_mfma_f32_16x16x32_bf16 v[92:95], v[138:141], v[194:197], v[92:95]
	v_mfma_f32_16x16x32_bf16 v[88:91], v[152:155], v[194:197], v[88:91]
	v_mfma_f32_16x16x32_bf16 v[76:79], v[138:141], v[202:205], v[76:79]
	v_mfma_f32_16x16x32_bf16 v[72:75], v[152:155], v[202:205], v[72:75]
	v_mfma_f32_16x16x32_bf16 v[124:127], v[148:151], v[180:183], v[124:127]
	v_mfma_f32_16x16x32_bf16 v[120:123], v[156:159], v[180:183], v[120:123]
	v_mfma_f32_16x16x32_bf16 v[108:111], v[148:151], v[188:191], v[108:111]
	v_mfma_f32_16x16x32_bf16 v[104:107], v[156:159], v[188:191], v[104:107]
	v_mfma_f32_16x16x32_bf16 v[92:95], v[148:151], v[198:201], v[92:95]
	v_mfma_f32_16x16x32_bf16 v[88:91], v[156:159], v[198:201], v[88:91]
	v_mfma_f32_16x16x32_bf16 v[76:79], v[148:151], v[206:209], v[76:79]
	v_mfma_f32_16x16x32_bf16 v[72:75], v[156:159], v[206:209], v[72:75]
	s_setprio 0
	s_setprio 1
	v_mfma_f32_16x16x32_bf16 v[116:119], v[160:163], v[176:179], v[116:119]
	v_mfma_f32_16x16x32_bf16 v[112:115], v[168:171], v[176:179], v[112:115]
	v_mfma_f32_16x16x32_bf16 v[100:103], v[160:163], v[184:187], v[100:103]
	v_mfma_f32_16x16x32_bf16 v[96:99], v[168:171], v[184:187], v[96:99]
	v_mfma_f32_16x16x32_bf16 v[84:87], v[160:163], v[194:197], v[84:87]
	v_mfma_f32_16x16x32_bf16 v[80:83], v[168:171], v[194:197], v[80:83]
	v_mfma_f32_16x16x32_bf16 v[68:71], v[160:163], v[202:205], v[68:71]
	v_mfma_f32_16x16x32_bf16 v[64:67], v[168:171], v[202:205], v[64:67]
	v_mfma_f32_16x16x32_bf16 v[116:119], v[164:167], v[180:183], v[116:119]
	v_mfma_f32_16x16x32_bf16 v[112:115], v[172:175], v[180:183], v[112:115]
	v_mfma_f32_16x16x32_bf16 v[100:103], v[164:167], v[188:191], v[100:103]
	v_mfma_f32_16x16x32_bf16 v[96:99], v[172:175], v[188:191], v[96:99]
	v_mfma_f32_16x16x32_bf16 v[84:87], v[164:167], v[198:201], v[84:87]
	v_mfma_f32_16x16x32_bf16 v[80:83], v[172:175], v[198:201], v[80:83]
	v_mfma_f32_16x16x32_bf16 v[68:71], v[164:167], v[206:209], v[68:71]
	v_mfma_f32_16x16x32_bf16 v[64:67], v[172:175], v[206:209], v[64:67]
	s_barrier
	s_setprio 0
	s_add_i32 s26, s26, s69
	v_lshl_add_u64 v[210:211], s[80:81], 0, v[192:193]
	s_mov_b32 m0, s26
	ds_read_b128 v[176:179], v147 offset:16384
	ds_read_b128 v[180:183], v147 offset:17408
	ds_read_b128 v[184:187], v147 offset:18432
	ds_read_b128 v[188:191], v147 offset:19456
	ds_read_b128 v[194:197], v147 offset:20480
	ds_read_b128 v[198:201], v147 offset:21504
	ds_read_b128 v[202:205], v147 offset:22528
	ds_read_b128 v[206:209], v147 offset:23552
	global_load_lds_dwordx4 v[210:211], off
	s_add_i32 m0, s26, 0x2000
	s_add_u32 s26, s80, 0xb0000
	v_lshl_add_u64 v[212:213], s[80:81], 0, v[132:133]
	s_addc_u32 s27, s81, 0
	s_add_i32 s65, s65, s69
	global_load_lds_dwordx4 v[212:213], off
	v_lshl_add_u64 v[214:215], s[26:27], 0, v[192:193]
	s_mov_b32 m0, s65
	v_lshl_add_u64 v[220:221], s[82:83], 0, v[130:131]
	global_load_lds_dwordx4 v[214:215], off
	v_lshl_add_u64 v[214:215], s[26:27], 0, v[132:133]
	s_add_i32 m0, s65, 0x2000
	s_nop 0
	global_load_lds_dwordx4 v[214:215], off
	v_lshl_add_u64 v[214:215], s[82:83], 0, v[128:129]
	s_mov_b32 m0, s84
	s_nop 0
	global_load_lds_dwordx4 v[214:215], off
	s_mov_b32 m0, s85
	s_nop 0
	global_load_lds_dwordx4 v[220:221], off
	s_waitcnt vmcnt(8)
	s_waitcnt lgkmcnt(0)
	s_barrier
; #define PG8_STAGE(bufoff, gbase, voff) do { _Pragma("unroll") for (int _i = 0; _i < 2; ++_i) \
;         __builtin_amdgcn_global_load_lds((const unsigned*)((const char*)(gbase) + (voff)[_i]), (PG8_LAS unsigned*)(lds + (bufoff) + ldsw + _i * 8192), 16, 0, 0); } while (0)
; #define PG8_LDA(dst, b, h) do { _Pragma("unroll") for (int m = 0; m < 4; ++m) _Pragma("unroll") for (int k = 0; k < 2; ++k) dst[m][k] = *(const PG8_LAS bf16x8*)(lds + PG8_SA(b, h) + aoff + m * 2048 + k * 1024); } while (0)
; #define PG8_LDB(dst, b, h) do { _Pragma("unroll") for (int n = 0; n < 2; ++n) _Pragma("unroll") for (int k = 0; k < 2; ++k) dst[n][k] = *(const PG8_LAS bf16x8*)(lds + PG8_SB(b, h) + boff + n * 2048 + k * 1024); } while (0)
; #define PG8_MMA(ai, bj, At, Bt) do { __builtin_amdgcn_s_setprio(1); _Pragma("unroll") for (int m = 0; m < 4; ++m) _Pragma("unroll") for (int n = 0; n < 2; ++n) _Pragma("unroll") for (int k = 0; k < 2; ++k) \
;         acc[ai][bj][m][n] = __builtin_amdgcn_mfma_f32_16x16x32_bf16(Bt[n][k], At[m][k], acc[ai][bj][m][n], 0, 0, 0); __builtin_amdgcn_s_setprio(0); } while (0)
; #define PG8_WAIT_V(n) asm volatile("s_waitcnt vmcnt(" #n ")" ::: "memory")
; #define PG8_WAIT_L(n) asm volatile("s_waitcnt lgkmcnt(" #n ")" ::: "memory")
; #define PG8_BAR __builtin_amdgcn_s_barrier()
; #define PG8_SCHED __builtin_amdgcn_sched_barrier(0)
; template <class Epi, class Sched, bool ALIGN_EPI = false, bool SP2 = false>
; __device__ __forceinline__ void gemm_phase(PG8_LAS unsigned char* lds, const Gemm g, const Sched& S, const Epi& E, int wid0) {
;     ...
;             PG8_WAIT_V(8); PG8_WAIT_L(0); PG8_BAR; PG8_MMA(1, 0, At, B0); PG8_MMA(1, 1, At, B1); PG8_BAR; PG8_SCHED;
;             PG8_LDB(B0, 1, 0); PG8_LDB(B1, 1, 1); PG8_SCHED; PG8_LDA(At, 1, 0); PG8_STAGE(PG8_SA(0, 1), a2 + hstep, voffA);
;             PG8_WAIT_V(8); PG8_WAIT_L(0); PG8_BAR; PG8_MMA(0, 0, At, B0); PG8_MMA(0, 1, At, B1); PG8_BAR; PG8_SCHED;
	s_setprio 1
	s_waitcnt lgkmcnt(0)
	v_mfma_f32_16x16x32_bf16 v[60:63], v[138:141], v[176:179], v[60:63]
	v_mfma_f32_16x16x32_bf16 v[56:59], v[152:155], v[176:179], v[56:59]
	v_mfma_f32_16x16x32_bf16 v[44:47], v[138:141], v[184:187], v[44:47]
	v_mfma_f32_16x16x32_bf16 v[40:43], v[152:155], v[184:187], v[40:43]
	v_mfma_f32_16x16x32_bf16 v[28:31], v[138:141], v[194:197], v[28:31]
	v_mfma_f32_16x16x32_bf16 v[24:27], v[152:155], v[194:197], v[24:27]
	v_mfma_f32_16x16x32_bf16 v[12:15], v[138:141], v[202:205], v[12:15]
	v_mfma_f32_16x16x32_bf16 v[8:11], v[152:155], v[202:205], v[8:11]
	v_mfma_f32_16x16x32_bf16 v[60:63], v[148:151], v[180:183], v[60:63]
	v_mfma_f32_16x16x32_bf16 v[56:59], v[156:159], v[180:183], v[56:59]
	v_mfma_f32_16x16x32_bf16 v[44:47], v[148:151], v[188:191], v[44:47]
	v_mfma_f32_16x16x32_bf16 v[40:43], v[156:159], v[188:191], v[40:43]
	v_mfma_f32_16x16x32_bf16 v[28:31], v[148:151], v[198:201], v[28:31]
	v_mfma_f32_16x16x32_bf16 v[24:27], v[156:159], v[198:201], v[24:27]
	v_mfma_f32_16x16x32_bf16 v[12:15], v[148:151], v[206:209], v[12:15]
	v_mfma_f32_16x16x32_bf16 v[8:11], v[156:159], v[206:209], v[8:11]
	s_setprio 0
	s_setprio 1
	v_mfma_f32_16x16x32_bf16 v[52:55], v[160:163], v[176:179], v[52:55]
	v_mfma_f32_16x16x32_bf16 v[48:51], v[168:171], v[176:179], v[48:51]
	v_mfma_f32_16x16x32_bf16 v[36:39], v[160:163], v[184:187], v[36:39]
	v_mfma_f32_16x16x32_bf16 v[32:35], v[168:171], v[184:187], v[32:35]
	v_mfma_f32_16x16x32_bf16 v[20:23], v[160:163], v[194:197], v[20:23]
	v_mfma_f32_16x16x32_bf16 v[16:19], v[168:171], v[194:197], v[16:19]
	v_mfma_f32_16x16x32_bf16 v[4:7], v[160:163], v[202:205], v[4:7]
	v_mfma_f32_16x16x32_bf16 v[0:3], v[168:171], v[202:205], v[0:3]
	v_mfma_f32_16x16x32_bf16 v[52:55], v[164:167], v[180:183], v[52:55]
	v_mfma_f32_16x16x32_bf16 v[48:51], v[172:175], v[180:183], v[48:51]
	v_mfma_f32_16x16x32_bf16 v[36:39], v[164:167], v[188:191], v[36:39]
	v_mfma_f32_16x16x32_bf16 v[32:35], v[172:175], v[188:191], v[32:35]
	v_mfma_f32_16x16x32_bf16 v[20:23], v[164:167], v[198:201], v[20:23]
	v_mfma_f32_16x16x32_bf16 v[16:19], v[172:175], v[198:201], v[16:19]
	v_mfma_f32_16x16x32_bf16 v[4:7], v[164:167], v[206:209], v[4:7]
	v_mfma_f32_16x16x32_bf16 v[0:3], v[172:175], v[206:209], v[0:3]
	s_barrier
	s_setprio 0
	s_add_i32 s65, 0, 0x18000
	s_add_i32 s66, 0, 0x1c000
	v_add_u32_e32 v156, s65, v143
	v_add_u32_e32 v172, s66, v143
	ds_read_b128 v[138:141], v156
	ds_read_b128 v[148:151], v156 offset:1024
	ds_read_b128 v[152:155], v156 offset:2048
	ds_read_b128 v[156:159], v156 offset:3072
	ds_read_b128 v[160:163], v172
	ds_read_b128 v[164:167], v172 offset:1024
	ds_read_b128 v[168:171], v172 offset:2048
	ds_read_b128 v[172:175], v172 offset:3072
	s_add_u32 s26, s82, 0xb0000
	s_addc_u32 s27, s83, 0
	s_mov_b32 m0, s86
	v_lshl_add_u64 v[222:223], s[26:27], 0, v[128:129]
	ds_read_b128 v[176:179], v147 offset:32768
	ds_read_b128 v[180:183], v147 offset:33792
	ds_read_b128 v[184:187], v147 offset:34816
	ds_read_b128 v[188:191], v147 offset:35840
	ds_read_b128 v[194:197], v147 offset:36864
	ds_read_b128 v[198:201], v147 offset:37888
	ds_read_b128 v[202:205], v147 offset:38912
	ds_read_b128 v[206:209], v147 offset:39936
	global_load_lds_dwordx4 v[222:223], off
	v_lshl_add_u64 v[222:223], s[26:27], 0, v[130:131]
	s_mov_b32 m0, s87
	s_nop 0
	global_load_lds_dwordx4 v[222:223], off
	s_waitcnt vmcnt(8)
	s_waitcnt lgkmcnt(0)
	s_barrier
	s_setprio 1
	s_waitcnt lgkmcnt(0)
	v_mfma_f32_16x16x32_bf16 v[124:127], v[138:141], v[176:179], v[124:127]
	v_mfma_f32_16x16x32_bf16 v[120:123], v[152:155], v[176:179], v[120:123]
	v_mfma_f32_16x16x32_bf16 v[108:111], v[138:141], v[184:187], v[108:111]
	v_mfma_f32_16x16x32_bf16 v[104:107], v[152:155], v[184:187], v[104:107]
	v_mfma_f32_16x16x32_bf16 v[92:95], v[138:141], v[194:197], v[92:95]
	v_mfma_f32_16x16x32_bf16 v[88:91], v[152:155], v[194:197], v[88:91]
	v_mfma_f32_16x16x32_bf16 v[76:79], v[138:141], v[202:205], v[76:79]
	v_mfma_f32_16x16x32_bf16 v[72:75], v[152:155], v[202:205], v[72:75]
	v_mfma_f32_16x16x32_bf16 v[124:127], v[148:151], v[180:183], v[124:127]
	v_mfma_f32_16x16x32_bf16 v[120:123], v[156:159], v[180:183], v[120:123]
	v_mfma_f32_16x16x32_bf16 v[108:111], v[148:151], v[188:191], v[108:111]
	v_mfma_f32_16x16x32_bf16 v[104:107], v[156:159], v[188:191], v[104:107]
	v_mfma_f32_16x16x32_bf16 v[92:95], v[148:151], v[198:201], v[92:95]
	v_mfma_f32_16x16x32_bf16 v[88:91], v[156:159], v[198:201], v[88:91]
	v_mfma_f32_16x16x32_bf16 v[76:79], v[148:151], v[206:209], v[76:79]
	v_mfma_f32_16x16x32_bf16 v[72:75], v[156:159], v[206:209], v[72:75]
	s_setprio 0
	s_setprio 1
	v_mfma_f32_16x16x32_bf16 v[116:119], v[160:163], v[176:179], v[116:119]
	v_mfma_f32_16x16x32_bf16 v[112:115], v[168:171], v[176:179], v[112:115]
	v_mfma_f32_16x16x32_bf16 v[100:103], v[160:163], v[184:187], v[100:103]
	v_mfma_f32_16x16x32_bf16 v[96:99], v[168:171], v[184:187], v[96:99]
	v_mfma_f32_16x16x32_bf16 v[84:87], v[160:163], v[194:197], v[84:87]
	v_mfma_f32_16x16x32_bf16 v[80:83], v[168:171], v[194:197], v[80:83]
	v_mfma_f32_16x16x32_bf16 v[68:71], v[160:163], v[202:205], v[68:71]
	v_mfma_f32_16x16x32_bf16 v[64:67], v[168:171], v[202:205], v[64:67]
	v_mfma_f32_16x16x32_bf16 v[116:119], v[164:167], v[180:183], v[116:119]
	v_mfma_f32_16x16x32_bf16 v[112:115], v[172:175], v[180:183], v[112:115]
	v_mfma_f32_16x16x32_bf16 v[100:103], v[164:167], v[188:191], v[100:103]
	v_mfma_f32_16x16x32_bf16 v[96:99], v[172:175], v[188:191], v[96:99]
	v_mfma_f32_16x16x32_bf16 v[84:87], v[164:167], v[198:201], v[84:87]
	v_mfma_f32_16x16x32_bf16 v[80:83], v[172:175], v[198:201], v[80:83]
	v_mfma_f32_16x16x32_bf16 v[68:71], v[164:167], v[206:209], v[68:71]
	v_mfma_f32_16x16x32_bf16 v[64:67], v[172:175], v[206:209], v[64:67]
	s_barrier
; #define PG8_STAGE(bufoff, gbase, voff) do { _Pragma("unroll") for (int _i = 0; _i < 2; ++_i) \
;         __builtin_amdgcn_global_load_lds((const unsigned*)((const char*)(gbase) + (voff)[_i]), (PG8_LAS unsigned*)(lds + (bufoff) + ldsw + _i * 8192), 16, 0, 0); } while (0)
; #define PG8_LDA(dst, b, h) do { _Pragma("unroll") for (int m = 0; m < 4; ++m) _Pragma("unroll") for (int k = 0; k < 2; ++k) dst[m][k] = *(const PG8_LAS bf16x8*)(lds + PG8_SA(b, h) + aoff + m * 2048 + k * 1024); } while (0)
; #define PG8_MMA(ai, bj, At, Bt) do { __builtin_amdgcn_s_setprio(1); _Pragma("unroll") for (int m = 0; m < 4; ++m) _Pragma("unroll") for (int n = 0; n < 2; ++n) _Pragma("unroll") for (int k = 0; k < 2; ++k) \
;         acc[ai][bj][m][n] = __builtin_amdgcn_mfma_f32_16x16x32_bf16(Bt[n][k], At[m][k], acc[ai][bj][m][n], 0, 0, 0); __builtin_amdgcn_s_setprio(0); } while (0)
; #define PG8_WAIT_V(n) asm volatile("s_waitcnt vmcnt(" #n ")" ::: "memory")
; #define PG8_WAIT_L(n) asm volatile("s_waitcnt lgkmcnt(" #n ")" ::: "memory")
; #define PG8_BAR __builtin_amdgcn_s_barrier()
; #define PG8_SCHED __builtin_amdgcn_sched_barrier(0)
; template <class Epi, class Sched, bool ALIGN_EPI = false, bool SP2 = false>
; __device__ __forceinline__ void gemm_phase(PG8_LAS unsigned char* lds, const Gemm g, const Sched& S, const Epi& E, int wid0) {
;     ...
;             PG8_LDA(At, 1, 1); PG8_STAGE(PG8_SB(1, 0), b3, voffB); PG8_STAGE(PG8_SB(1, 1), b3 + hstep, voffB); PG8_STAGE(PG8_SA(1, 0), a3, voffA);
;             PG8_WAIT_V(8); PG8_WAIT_L(0); PG8_BAR; PG8_MMA(1, 0, At, B0); PG8_MMA(1, 1, At, B1); PG8_BAR; PG8_SCHED;
;     ...
;         if constexpr (ALIGN_EPI) { if (wr == 0) PG8_BAR; }
	s_setprio 0
	s_add_i32 s26, s65, s69
	v_lshl_add_u64 v[210:211], v[210:211], 0, s[30:31]
	s_mov_b32 m0, s26
	ds_read_b128 v[176:179], v147 offset:49152
	ds_read_b128 v[180:183], v147 offset:50176
	ds_read_b128 v[184:187], v147 offset:51200
	ds_read_b128 v[188:191], v147 offset:52224
	ds_read_b128 v[194:197], v147 offset:53248
	ds_read_b128 v[198:201], v147 offset:54272
	ds_read_b128 v[202:205], v147 offset:55296
	ds_read_b128 v[206:209], v147 offset:56320
	global_load_lds_dwordx4 v[210:211], off
	s_add_i32 m0, s26, 0x2000
	s_add_u32 s26, s80, 0xb0080
	v_lshl_add_u64 v[210:211], v[212:213], 0, s[30:31]
	s_addc_u32 s27, s81, 0
	s_add_i32 s65, s66, s69
	global_load_lds_dwordx4 v[210:211], off
	v_lshl_add_u64 v[210:211], s[26:27], 0, v[192:193]
	s_mov_b32 m0, s65
	s_nop 0
	global_load_lds_dwordx4 v[210:211], off
	v_lshl_add_u64 v[210:211], s[26:27], 0, v[132:133]
	s_add_i32 m0, s65, 0x2000
	s_nop 0
	global_load_lds_dwordx4 v[210:211], off
	v_lshl_add_u64 v[210:211], v[214:215], 0, s[30:31]
	s_mov_b32 m0, s89
	s_nop 0
	global_load_lds_dwordx4 v[210:211], off
	v_lshl_add_u64 v[210:211], v[220:221], 0, s[30:31]
	s_mov_b32 m0, s90
	s_nop 0
	global_load_lds_dwordx4 v[210:211], off
	s_waitcnt vmcnt(8)
	s_waitcnt lgkmcnt(0)
	s_barrier
	s_setprio 1
	s_waitcnt lgkmcnt(0)
	v_mfma_f32_16x16x32_bf16 v[60:63], v[138:141], v[176:179], v[60:63]
	v_mfma_f32_16x16x32_bf16 v[56:59], v[152:155], v[176:179], v[56:59]
	v_mfma_f32_16x16x32_bf16 v[44:47], v[138:141], v[184:187], v[44:47]
	v_mfma_f32_16x16x32_bf16 v[40:43], v[152:155], v[184:187], v[40:43]
	v_mfma_f32_16x16x32_bf16 v[28:31], v[138:141], v[194:197], v[28:31]
	v_mfma_f32_16x16x32_bf16 v[24:27], v[152:155], v[194:197], v[24:27]
	v_mfma_f32_16x16x32_bf16 v[12:15], v[138:141], v[202:205], v[12:15]
	v_mfma_f32_16x16x32_bf16 v[8:11], v[152:155], v[202:205], v[8:11]
	v_mfma_f32_16x16x32_bf16 v[60:63], v[148:151], v[180:183], v[60:63]
	v_mfma_f32_16x16x32_bf16 v[56:59], v[156:159], v[180:183], v[56:59]
	v_mfma_f32_16x16x32_bf16 v[44:47], v[148:151], v[188:191], v[44:47]
	v_mfma_f32_16x16x32_bf16 v[40:43], v[156:159], v[188:191], v[40:43]
	v_mfma_f32_16x16x32_bf16 v[28:31], v[148:151], v[198:201], v[28:31]
	v_mfma_f32_16x16x32_bf16 v[24:27], v[156:159], v[198:201], v[24:27]
	v_mfma_f32_16x16x32_bf16 v[12:15], v[148:151], v[206:209], v[12:15]
	v_mfma_f32_16x16x32_bf16 v[8:11], v[156:159], v[206:209], v[8:11]
	s_setprio 0
	s_setprio 1
	v_mfma_f32_16x16x32_bf16 v[52:55], v[160:163], v[176:179], v[52:55]
	v_mfma_f32_16x16x32_bf16 v[48:51], v[168:171], v[176:179], v[48:51]
	v_mfma_f32_16x16x32_bf16 v[36:39], v[160:163], v[184:187], v[36:39]
	v_mfma_f32_16x16x32_bf16 v[32:35], v[168:171], v[184:187], v[32:35]
	v_mfma_f32_16x16x32_bf16 v[20:23], v[160:163], v[194:197], v[20:23]
	v_mfma_f32_16x16x32_bf16 v[16:19], v[168:171], v[194:197], v[16:19]
	v_mfma_f32_16x16x32_bf16 v[4:7], v[160:163], v[202:205], v[4:7]
	v_mfma_f32_16x16x32_bf16 v[0:3], v[168:171], v[202:205], v[0:3]
	v_mfma_f32_16x16x32_bf16 v[52:55], v[164:167], v[180:183], v[52:55]
	v_mfma_f32_16x16x32_bf16 v[48:51], v[172:175], v[180:183], v[48:51]
	v_mfma_f32_16x16x32_bf16 v[36:39], v[164:167], v[188:191], v[36:39]
	v_mfma_f32_16x16x32_bf16 v[32:35], v[172:175], v[188:191], v[32:35]
	v_mfma_f32_16x16x32_bf16 v[20:23], v[164:167], v[198:201], v[20:23]
	v_mfma_f32_16x16x32_bf16 v[16:19], v[172:175], v[198:201], v[16:19]
	v_mfma_f32_16x16x32_bf16 v[4:7], v[164:167], v[206:209], v[4:7]
	v_mfma_f32_16x16x32_bf16 v[0:3], v[172:175], v[206:209], v[0:3]
	s_barrier
	s_setprio 0
	s_add_i32 s64, s64, 2
	s_add_u32 s10, s10, 0x100
	s_addc_u32 s11, s11, 0
	s_cmp_gt_u32 s64, 41
	s_mov_b64 s[76:77], s[78:79]
	s_cbranch_scc0 .LBB0_630
	s_and_b64 vcc, exec, s[72:73]
	s_cbranch_vccz .LBB0_633
	s_barrier
